# wave-level GEMM K-loops (kidx, S1, S5, memK/V, S7, S9, S11, S12): all fragment loads of a K pass issued up front with counted waits instead of load-wait-MFMA chains; plus S4 compaction prefetch
# baseline (speedup 1.0000x reference)
; __device__ __forceinline__ int crow(int r, int hi) { return (r & 3) + 8 * (r >> 2) + 4 * hi; }
; __device__ __forceinline__ int crow(int r, int hi) { return (r & 3) + 8 * (r >> 2) + 4 * hi; }
;     ...
;     for (int it = (int)blockIdx.x - wg_lo; it < NIT; it += wg_n) { const int ks = it / nT, it2 = it % nT, mb = it2 % nMb, nbk = it2 / nMb, row0 = 32 * mb, col0 = 64 * nbk, kbeg = (ks * 8 + wave) * KW;
;         f32x16 acc0 = {}, acc1 = {};
;         const bf16* b0p = Bt + (size_t)(col0 + r32) * K + 16 * hh + kbeg; const bf16* b1p = b0p + (size_t)32 * K; const float* af = (const float*)Av + (size_t)(row0 + r32) * lda + 16 * hh + kbeg; const bf16* ab = (const bf16*)Av + (size_t)(row0 + r32) * lda + 16 * hh + kbeg;
; #pragma unroll
;         for (int k0 = 0; k0 < KW; k0 += 32) { bf16x8 a0, a1;
;           if (ABF) { a0 = *(const bf16x8*)(ab + k0); a1 = *(const bf16x8*)(ab + k0 + 8); } else {
;             const f32x4 x0 = *(const f32x4*)(af + k0), x1 = *(const f32x4*)(af + k0 + 4), x2 = *(const f32x4*)(af + k0 + 8), x3 = *(const f32x4*)(af + k0 + 12);
;             const u32x4_t p0 = {cvtpk(x0[0], x0[1]), cvtpk(x0[2], x0[3]), cvtpk(x1[0], x1[1]), cvtpk(x1[2], x1[3])}, p1 = {cvtpk(x2[0], x2[1]), cvtpk(x2[2], x2[3]), cvtpk(x3[0], x3[1]), cvtpk(x3[2], x3[3])};
;             a0 = __builtin_bit_cast(bf16x8, p0); a1 = __builtin_bit_cast(bf16x8, p1); }
;             const bf16x8 b00 = *(const bf16x8*)(b0p + k0), b01 = *(const bf16x8*)(b0p + k0 + 8), b10 = *(const bf16x8*)(b1p + k0), b11 = *(const bf16x8*)(b1p + k0 + 8);
;             acc0 = __builtin_amdgcn_mfma_f32_32x32x16_bf16(a0, b00, acc0, 0, 0, 0); acc0 = __builtin_amdgcn_mfma_f32_32x32x16_bf16(a1, b01, acc0, 0, 0, 0);
;             acc1 = __builtin_amdgcn_mfma_f32_32x32x16_bf16(a0, b10, acc1, 0, 0, 0); acc1 = __builtin_amdgcn_mfma_f32_32x32x16_bf16(a1, b11, acc1, 0, 0, 0); }
; #pragma unroll
;         for (int rg = 0; rg < 16; ++rg) { red[wave * 2048 + rg * 64 + lane] = acc0[rg]; red[wave * 2048 + (16 + rg) * 64 + lane] = acc1[rg]; }
;         __syncthreads();
; #pragma unroll
;         for (int q = 0; q < 4; ++q) { const int rr = 4 * wave + q; float v = 0.f;
; #pragma unroll
;             for (int w = 0; w < 8; ++w) v += red[w * 2048 + rr * 64 + lane];
;             E.el(row0 + crow(rr & 15, hh), col0 + (rr >> 4) * 32 + r32, v, r32); }
.LBB0_363:
	s_ashr_i32 s4, s15, 31
	s_lshr_b32 s4, s4, 23
	s_add_i32 s4, s15, s4
	s_ashr_i32 s16, s4, 9
	s_lshl_b32 s4, s16, 10
	s_add_i32 s4, s4, s10
	s_ashr_i32 s5, s4, 31
	s_lshl_b64 s[8:9], s[4:5], 1
	s_lshl_b32 s4, s16, 14
	s_sub_i32 s4, s14, s4
	v_add_u32_e32 v2, s4, v34
	v_ashrrev_i32_e32 v3, 31, v2
	v_lshlrev_b64 v[2:3], 11, v[2:3]
	v_lshl_add_u64 v[2:3], v[38:39], 0, v[2:3]
	v_lshl_add_u64 v[60:61], v[2:3], 0, s[8:9]
	global_load_dwordx4 v[66:69], v[60:61], off
	v_lshl_add_u64 v[62:63], v[36:37], 0, s[8:9]
	global_load_dwordx4 v[84:87], v[62:63], off
	v_add_co_u32_e64 v64, s[8:9], s47, v62
	s_nop 1
	v_addc_co_u32_e64 v65, s[8:9], 0, v63, s[8:9]
	global_load_dwordx4 v[88:91], v[64:65], off
	global_load_dwordx4 v[92:95], v[60:61], off offset:16
	global_load_dwordx4 v[96:99], v[62:63], off offset:16
	global_load_dwordx4 v[100:103], v[64:65], off offset:16
	global_load_dwordx4 v[104:107], v[60:61], off offset:64
	global_load_dwordx4 v[108:111], v[62:63], off offset:64
	global_load_dwordx4 v[112:115], v[64:65], off offset:64
	global_load_dwordx4 v[116:119], v[60:61], off offset:80
	global_load_dwordx4 v[120:123], v[62:63], off offset:80
	global_load_dwordx4 v[124:127], v[64:65], off offset:80
	global_load_dwordx4 v[128:131], v[60:61], off offset:128
	s_waitcnt vmcnt(11)
	v_mfma_f32_32x32x16_bf16 v[2:17], v[66:69], v[84:87], 0
	s_waitcnt vmcnt(8)
	v_mfma_f32_32x32x16_bf16 v[2:17], v[92:95], v[96:99], v[2:17]
	v_mfma_f32_32x32x16_bf16 v[18:33], v[66:69], v[88:91], 0
	s_waitcnt vmcnt(7)
	v_mfma_f32_32x32x16_bf16 v[18:33], v[92:95], v[100:103], v[18:33]
	s_waitcnt vmcnt(5)
	v_mfma_f32_32x32x16_bf16 v[2:17], v[104:107], v[108:111], v[2:17]
	s_waitcnt vmcnt(4)
	v_mfma_f32_32x32x16_bf16 v[18:33], v[104:107], v[112:115], v[18:33]
	s_waitcnt vmcnt(2)
	v_mfma_f32_32x32x16_bf16 v[2:17], v[116:119], v[120:123], v[2:17]
	s_waitcnt vmcnt(1)
	v_mfma_f32_32x32x16_bf16 v[18:33], v[116:119], v[124:127], v[18:33]
	global_load_dwordx4 v[66:69], v[62:63], off offset:128
	global_load_dwordx4 v[84:87], v[64:65], off offset:128
	global_load_dwordx4 v[88:91], v[60:61], off offset:144
	global_load_dwordx4 v[92:95], v[62:63], off offset:144
	global_load_dwordx4 v[96:99], v[64:65], off offset:144
	global_load_dwordx4 v[100:103], v[60:61], off offset:192
	global_load_dwordx4 v[104:107], v[62:63], off offset:192
	global_load_dwordx4 v[108:111], v[64:65], off offset:192
	global_load_dwordx4 v[112:115], v[60:61], off offset:208
	global_load_dwordx4 v[116:119], v[62:63], off offset:208
	global_load_dwordx4 v[120:123], v[64:65], off offset:208
	s_waitcnt vmcnt(10)
	v_mfma_f32_32x32x16_bf16 v[2:17], v[128:131], v[66:69], v[2:17]
	s_waitcnt vmcnt(9)
	v_mfma_f32_32x32x16_bf16 v[18:33], v[128:131], v[84:87], v[18:33]
	s_waitcnt vmcnt(7)
	v_mfma_f32_32x32x16_bf16 v[2:17], v[88:91], v[92:95], v[2:17]
	s_waitcnt vmcnt(6)
	v_mfma_f32_32x32x16_bf16 v[18:33], v[88:91], v[96:99], v[18:33]
	s_waitcnt vmcnt(4)
	v_mfma_f32_32x32x16_bf16 v[2:17], v[100:103], v[104:107], v[2:17]
	s_waitcnt vmcnt(3)
	v_mfma_f32_32x32x16_bf16 v[18:33], v[100:103], v[108:111], v[18:33]
	s_waitcnt vmcnt(1)
	v_mfma_f32_32x32x16_bf16 v[2:17], v[112:115], v[116:119], v[2:17]
	s_waitcnt vmcnt(0)
	v_mfma_f32_32x32x16_bf16 v[18:33], v[112:115], v[120:123], v[18:33]
	s_nop 8
	ds_write2st64_b32 v43, v2, v3 offset1:1
	s_nop 1
	ds_write2st64_b32 v43, v18, v19 offset0:16 offset1:17
	ds_write2st64_b32 v43, v4, v5 offset0:2 offset1:3
	ds_write2st64_b32 v43, v20, v21 offset0:18 offset1:19
	ds_write2st64_b32 v43, v6, v7 offset0:4 offset1:5
	ds_write2st64_b32 v43, v22, v23 offset0:20 offset1:21
	ds_write2st64_b32 v43, v8, v9 offset0:6 offset1:7
	ds_write2st64_b32 v43, v24, v25 offset0:22 offset1:23
	ds_write2st64_b32 v43, v10, v11 offset0:8 offset1:9
	ds_write2st64_b32 v43, v26, v27 offset0:24 offset1:25
	ds_write2st64_b32 v43, v12, v13 offset0:10 offset1:11
	ds_write2st64_b32 v43, v28, v29 offset0:26 offset1:27
	ds_write2st64_b32 v43, v14, v15 offset0:12 offset1:13
	ds_write2st64_b32 v43, v30, v31 offset0:28 offset1:29
	ds_write2st64_b32 v43, v16, v17 offset0:14 offset1:15
	ds_write2st64_b32 v43, v32, v33 offset0:30 offset1:31
	s_waitcnt lgkmcnt(0)
	s_barrier
	ds_read2st64_b32 v[2:3], v46 offset1:32
	ds_read2st64_b32 v[4:5], v46 offset0:64 offset1:96
	ds_read2st64_b32 v[6:7], v46 offset0:128 offset1:160
	s_waitcnt lgkmcnt(2)
	v_add_f32_e32 v2, 0, v2
	v_add_f32_e32 v8, v2, v3
	ds_read2st64_b32 v[2:3], v46 offset0:192 offset1:224
	s_waitcnt lgkmcnt(2)
	v_add_f32_e32 v4, v8, v4
	v_add_f32_e32 v4, v4, v5
	s_waitcnt lgkmcnt(1)
	v_add_f32_e32 v4, v4, v6
	v_add_f32_e32 v4, v4, v7
	s_waitcnt lgkmcnt(0)
	v_add_f32_e32 v2, v4, v2
	v_add_f32_e32 v4, v2, v3
	ds_bpermute_b32 v3, v35, v4
	v_add_u32_e32 v2, s4, v44
	s_and_saveexec_b64 s[4:5], vcc
	s_xor_b64 s[4:5], exec, s[4:5]
	s_cbranch_execz .LBB0_367
	s_and_saveexec_b64 s[8:9], s[0:1]
	s_cbranch_execz .LBB0_366
	s_waitcnt lgkmcnt(0)
	v_ashrrev_i32_e32 v3, 31, v2
	v_lshlrev_b64 v[6:7], 5, v[2:3]
	v_lshl_add_u64 v[6:7], v[40:41], 0, v[6:7]
	v_mul_f32_e32 v3, 0x3eb504f3, v4
	global_store_dword v[6:7], v3, off

; #define LAS __attribute__((address_space(3)))
; __device__ __forceinline__ int crow(int r, int hi) { return (r & 3) + 8 * (r >> 2) + 4 * hi; }
; __device__ __forceinline__ int crow(int r, int hi) { return (r & 3) + 8 * (r >> 2) + 4 * hi; }
; __device__ __forceinline__ int crow(int r, int hi) { return (r & 3) + 8 * (r >> 2) + 4 * hi; }
; __device__ __forceinline__ int crow(int r, int hi) { return (r & 3) + 8 * (r >> 2) + 4 * hi; }
;     __device__ __forceinline__ void el(int row, int col, float v) const { if (col < nvalid) { if (act == 1) { v = v > 0.f ? v : 0.f; v = v * v; } C[(size_t)row * ldc + col] = v; } }
; template <class Epi>
; __device__ __forceinline__ void wgemm_wg_ln(const LnSrc& L, const bf16* Bt, int M, int N, const Epi& E, int G, int tid, LAS unsigned char* lds) {
;     ...
;     for (int nbk = cg; nbk < NBK; nbk += ncg) { const int col0 = 64 * nbk;
;         __syncthreads();
;         f32x16 acc0 = {}, acc1 = {}; const int kbeg = wave * KW;
;         const bf16* b0p = Bt + (size_t)(col0 + r32) * K + 16 * hh + kbeg; const bf16* b1p = b0p + (size_t)32 * K; LAS unsigned char* prow = panel + r32 * 2048;
; #pragma unroll
;         for (int k0 = 0; k0 < KW; k0 += 32) { const int ch = (kbeg + k0 + 16 * hh) >> 3;
;             const bf16x8 a0 = *(const LAS bf16x8*)(prow + ((ch ^ (r32 & 15)) << 4)), a1 = *(const LAS bf16x8*)(prow + (((ch + 1) ^ (r32 & 15)) << 4));
;             const bf16x8 b00 = *(const bf16x8*)(b0p + k0), b01 = *(const bf16x8*)(b0p + k0 + 8), b10 = *(const bf16x8*)(b1p + k0), b11 = *(const bf16x8*)(b1p + k0 + 8);
;             acc0 = __builtin_amdgcn_mfma_f32_32x32x16_bf16(a0, b00, acc0, 0, 0, 0); acc0 = __builtin_amdgcn_mfma_f32_32x32x16_bf16(a1, b01, acc0, 0, 0, 0);
;             acc1 = __builtin_amdgcn_mfma_f32_32x32x16_bf16(a0, b10, acc1, 0, 0, 0); acc1 = __builtin_amdgcn_mfma_f32_32x32x16_bf16(a1, b11, acc1, 0, 0, 0); }
; #pragma unroll
;         for (int rg = 0; rg < 16; ++rg) { red[wave * 2048 + rg * 64 + lane] = acc0[rg]; red[wave * 2048 + (16 + rg) * 64 + lane] = acc1[rg]; }
;         __syncthreads();
; #pragma unroll
;         for (int q = 0; q < 4; ++q) { const int rr = 4 * wave + q; float v = 0.f;
; #pragma unroll
;             for (int w = 0; w < 8; ++w) v += red[w * 2048 + rr * 64 + lane];
;             E.el(row0 + crow(rr & 15, hh), col0 + (rr >> 4) * 32 + r32, v, r32); }
.LBB0_424:
	v_add_u32_e32 v2, s17, v44
	v_ashrrev_i32_e32 v3, 31, v2
	v_lshlrev_b64 v[2:3], 11, v[2:3]
	v_lshl_add_u64 v[84:85], v[34:35], 0, v[2:3]
	s_waitcnt lgkmcnt(0)
	s_barrier
	ds_read_b128 v[18:21], v51
	ds_read_b128 v[60:63], v52
	global_load_dwordx4 v[88:91], v[84:85], off
	global_load_dwordx4 v[92:95], v[84:85], off offset:16
	v_add_co_u32_e32 v86, vcc, 0x10000, v84
	s_nop 1
	v_addc_co_u32_e32 v87, vcc, 0, v85, vcc
	global_load_dwordx4 v[96:99], v[86:87], off
	global_load_dwordx4 v[100:103], v[86:87], off offset:16
	global_load_dwordx4 v[104:107], v[84:85], off offset:64
	global_load_dwordx4 v[108:111], v[84:85], off offset:80
	global_load_dwordx4 v[112:115], v[86:87], off offset:64
	global_load_dwordx4 v[116:119], v[86:87], off offset:80
	global_load_dwordx4 v[120:123], v[84:85], off offset:128
	global_load_dwordx4 v[124:127], v[84:85], off offset:144
	global_load_dwordx4 v[128:131], v[86:87], off offset:128
	global_load_dwordx4 v[132:135], v[86:87], off offset:144
	global_load_dwordx4 v[136:139], v[84:85], off offset:192
	global_load_dwordx4 v[140:143], v[84:85], off offset:208
	global_load_dwordx4 v[150:153], v[86:87], off offset:192
	global_load_dwordx4 v[154:157], v[86:87], off offset:208
	s_add_i32 s12, s16, s17
	s_ashr_i32 s13, s12, 8
	s_cmpk_gt_u32 s12, 0xff
	s_cselect_b64 s[2:3], -1, 0
	s_cmp_lg_u32 s13, 2
	s_cselect_b64 s[6:7], -1, 0
	s_and_b64 s[2:3], s[2:3], s[6:7]
	s_add_i32 s6, s13, -7
	s_cmp_lt_u32 s6, 3
	s_cselect_b64 s[6:7], -1, 0
	s_cmp_eq_u32 s13, 11
	s_cselect_b64 s[8:9], -1, 0
	s_andn2_b32 s12, s12, 63
	s_cmp_eq_u32 s13, 2
	s_waitcnt lgkmcnt(1)
	s_waitcnt vmcnt(15)
	v_mfma_f32_32x32x16_bf16 v[2:17], v[18:21], v[88:91], 0
	s_waitcnt lgkmcnt(0)
	s_waitcnt vmcnt(14)
	v_mfma_f32_32x32x16_bf16 v[2:17], v[60:63], v[92:95], v[2:17]
	s_waitcnt vmcnt(13)
	v_mfma_f32_32x32x16_bf16 v[18:33], v[18:21], v[96:99], 0
	s_waitcnt vmcnt(12)
	v_mfma_f32_32x32x16_bf16 v[18:33], v[60:63], v[100:103], v[18:33]
	ds_read_b128 v[60:63], v53
	ds_read_b128 v[64:67], v54
	s_waitcnt lgkmcnt(1)
	s_waitcnt vmcnt(11)
	v_mfma_f32_32x32x16_bf16 v[2:17], v[60:63], v[104:107], v[2:17]
	s_waitcnt vmcnt(9)
	v_mfma_f32_32x32x16_bf16 v[18:33], v[60:63], v[112:115], v[18:33]
	s_waitcnt lgkmcnt(0)
	v_mfma_f32_32x32x16_bf16 v[2:17], v[64:67], v[108:111], v[2:17]
	s_waitcnt vmcnt(8)
	v_mfma_f32_32x32x16_bf16 v[18:33], v[64:67], v[116:119], v[18:33]
	ds_read_b128 v[60:63], v55
	ds_read_b128 v[64:67], v56
	s_waitcnt lgkmcnt(1)
	s_waitcnt vmcnt(7)
	v_mfma_f32_32x32x16_bf16 v[2:17], v[60:63], v[120:123], v[2:17]
	s_waitcnt vmcnt(5)
	v_mfma_f32_32x32x16_bf16 v[18:33], v[60:63], v[128:131], v[18:33]
	s_waitcnt lgkmcnt(0)
	v_mfma_f32_32x32x16_bf16 v[2:17], v[64:67], v[124:127], v[2:17]
	s_waitcnt vmcnt(4)
	v_mfma_f32_32x32x16_bf16 v[18:33], v[64:67], v[132:135], v[18:33]
	ds_read_b128 v[60:63], v57
	ds_read_b128 v[64:67], v58
	s_waitcnt lgkmcnt(1)
	s_waitcnt vmcnt(3)
	v_mfma_f32_32x32x16_bf16 v[2:17], v[60:63], v[136:139], v[2:17]
	s_waitcnt vmcnt(1)
	v_mfma_f32_32x32x16_bf16 v[18:33], v[60:63], v[150:153], v[18:33]
	s_waitcnt lgkmcnt(0)
	v_mfma_f32_32x32x16_bf16 v[2:17], v[64:67], v[140:143], v[2:17]
	s_waitcnt vmcnt(0)
	v_mfma_f32_32x32x16_bf16 v[18:33], v[64:67], v[154:157], v[18:33]
	s_nop 9
	ds_write2st64_b32 v48, v2, v3 offset1:1
	s_nop 0
	ds_write2st64_b32 v48, v18, v19 offset0:16 offset1:17
	ds_write2st64_b32 v48, v4, v5 offset0:2 offset1:3
	ds_write2st64_b32 v48, v20, v21 offset0:18 offset1:19
	ds_write2st64_b32 v48, v6, v7 offset0:4 offset1:5
	ds_write2st64_b32 v48, v22, v23 offset0:20 offset1:21
	ds_write2st64_b32 v48, v8, v9 offset0:6 offset1:7
	ds_write2st64_b32 v48, v24, v25 offset0:22 offset1:23
	ds_write2st64_b32 v48, v10, v11 offset0:8 offset1:9
	ds_write2st64_b32 v48, v26, v27 offset0:24 offset1:25
	ds_write2st64_b32 v48, v12, v13 offset0:10 offset1:11
	ds_write2st64_b32 v48, v28, v29 offset0:26 offset1:27
	ds_write2st64_b32 v48, v14, v15 offset0:12 offset1:13
	ds_write2st64_b32 v48, v30, v31 offset0:28 offset1:29
	ds_write2st64_b32 v48, v16, v17 offset0:14 offset1:15
	ds_write2st64_b32 v48, v32, v33 offset0:30 offset1:31
	v_add_u32_e32 v2, s17, v50
	v_lshrrev_b32_e32 v4, 1, v2
	v_and_b32_e32 v5, 28, v4
	v_or_b32_e32 v6, v5, v45
	v_add_u32_e32 v5, v46, v5
	v_cndmask_b32_e64 v5, v5, v6, s[0:1]
	v_add_u32_e32 v16, s12, v5
	s_cselect_b32 s12, 0x80, 0
	v_and_b32_e32 v4, 0x7c, v4
	s_waitcnt lgkmcnt(0)
	s_barrier
	v_add3_u32 v14, v47, v4, s12
	v_or3_b32 v15, v4, v45, s12
	ds_read2st64_b32 v[10:11], v59 offset1:32
	ds_read2st64_b32 v[8:9], v59 offset0:64 offset1:96
	ds_read2st64_b32 v[6:7], v59 offset0:128 offset1:160
	ds_read2st64_b32 v[4:5], v59 offset0:192 offset1:224
	v_cmp_gt_i32_e64 s[10:11], s21, v2
	v_add_u32_e32 v3, s17, v49
	v_mov_b32_e32 v12, v2
	s_and_saveexec_b64 s[12:13], s[10:11]
	s_cbranch_execz .LBB0_429
	s_mov_b64 s[14:15], -1
	s_and_b64 vcc, exec, s[2:3]
	s_cbranch_vccz .LBB0_427
	v_cndmask_b32_e64 v12, v2, v3, s[8:9]
	v_cndmask_b32_e64 v12, v12, v16, s[6:7]
	s_mov_b64 s[14:15], 0

; __device__ __forceinline__ int crow(int r, int hi) { return (r & 3) + 8 * (r >> 2) + 4 * hi; }
; __device__ __forceinline__ int crow(int r, int hi) { return (r & 3) + 8 * (r >> 2) + 4 * hi; }
;     ...
;     for (int it = (int)blockIdx.x - wg_lo; it < NIT; it += wg_n) { const int ks = it / nT, it2 = it % nT, mb = it2 % nMb, nbk = it2 / nMb, row0 = 32 * mb, col0 = 64 * nbk, kbeg = (ks * 8 + wave) * KW;
;         f32x16 acc0 = {}, acc1 = {};
;         const bf16* b0p = Bt + (size_t)(col0 + r32) * K + 16 * hh + kbeg; const bf16* b1p = b0p + (size_t)32 * K; const float* af = (const float*)Av + (size_t)(row0 + r32) * lda + 16 * hh + kbeg; const bf16* ab = (const bf16*)Av + (size_t)(row0 + r32) * lda + 16 * hh + kbeg;
; #pragma unroll
;         for (int k0 = 0; k0 < KW; k0 += 32) { bf16x8 a0, a1;
;           if (ABF) { a0 = *(const bf16x8*)(ab + k0); a1 = *(const bf16x8*)(ab + k0 + 8); } else {
;             const f32x4 x0 = *(const f32x4*)(af + k0), x1 = *(const f32x4*)(af + k0 + 4), x2 = *(const f32x4*)(af + k0 + 8), x3 = *(const f32x4*)(af + k0 + 12);
;             const u32x4_t p0 = {cvtpk(x0[0], x0[1]), cvtpk(x0[2], x0[3]), cvtpk(x1[0], x1[1]), cvtpk(x1[2], x1[3])}, p1 = {cvtpk(x2[0], x2[1]), cvtpk(x2[2], x2[3]), cvtpk(x3[0], x3[1]), cvtpk(x3[2], x3[3])};
;             a0 = __builtin_bit_cast(bf16x8, p0); a1 = __builtin_bit_cast(bf16x8, p1); }
;             const bf16x8 b00 = *(const bf16x8*)(b0p + k0), b01 = *(const bf16x8*)(b0p + k0 + 8), b10 = *(const bf16x8*)(b1p + k0), b11 = *(const bf16x8*)(b1p + k0 + 8);
;             acc0 = __builtin_amdgcn_mfma_f32_32x32x16_bf16(a0, b00, acc0, 0, 0, 0); acc0 = __builtin_amdgcn_mfma_f32_32x32x16_bf16(a1, b01, acc0, 0, 0, 0);
;             acc1 = __builtin_amdgcn_mfma_f32_32x32x16_bf16(a0, b10, acc1, 0, 0, 0); acc1 = __builtin_amdgcn_mfma_f32_32x32x16_bf16(a1, b11, acc1, 0, 0, 0); }
; #pragma unroll
;         for (int rg = 0; rg < 16; ++rg) { red[wave * 2048 + rg * 64 + lane] = acc0[rg]; red[wave * 2048 + (16 + rg) * 64 + lane] = acc1[rg]; }
;         __syncthreads();
; #pragma unroll
;         for (int q = 0; q < 4; ++q) { const int rr = 4 * wave + q; float v = 0.f;
; #pragma unroll
;             for (int w = 0; w < 8; ++w) v += red[w * 2048 + rr * 64 + lane];
;             E.el(row0 + crow(rr & 15, hh), col0 + (rr >> 4) * 32 + r32, v, r32); }
.LBB0_457:
	s_mul_hi_i32 s0, s18, 0x5397829d
	s_lshr_b32 s1, s0, 31
	s_ashr_i32 s0, s0, 7
	s_add_i32 s1, s0, s1
	s_mul_i32 s0, s1, 0xfffffe78
	s_add_i32 s0, s18, s0
	s_bfe_u32 s2, s0, 0x3001c
	s_add_i32 s2, s0, s2
	s_sext_i32_i16 s3, s2
	s_and_b32 s2, s2, 0xfff8
	s_sub_i32 s0, s0, s2
	s_sext_i32_i16 s0, s0
	s_lshl_b32 s19, s0, 5
	s_lshl_b32 s0, s3, 3
	s_andn2_b32 s0, s0, 63
	v_or_b32_e32 v2, s0, v44
	s_lshl_b32 s1, s1, 10
	v_ashrrev_i32_e32 v3, 31, v2
	s_add_i32 s2, s1, s16
	v_lshlrev_b64 v[2:3], 11, v[2:3]
	v_lshl_add_u64 v[2:3], v[34:35], 0, v[2:3]
	s_ashr_i32 s3, s2, 31
	v_lshl_add_u64 v[38:39], s[2:3], 1, v[2:3]
	v_or_b32_e32 v2, s19, v44
	v_ashrrev_i32_e32 v3, 31, v2
	v_lshlrev_b64 v[2:3], 12, v[2:3]
	v_lshl_add_u64 v[2:3], v[36:37], 0, v[2:3]
	v_lshl_add_u64 v[42:43], s[2:3], 2, v[2:3]
	global_load_dwordx4 v[84:87], v[42:43], off offset:48
	global_load_dwordx4 v[88:91], v[42:43], off offset:32
	global_load_dwordx4 v[92:95], v[42:43], off offset:16
	global_load_dwordx4 v[96:99], v[42:43], off
	v_add_co_u32_e32 v40, vcc, s47, v38
	s_nop 1
	v_addc_co_u32_e32 v41, vcc, 0, v39, vcc
	global_load_dwordx4 v[100:103], v[38:39], off
	global_load_dwordx4 v[104:107], v[38:39], off offset:16
	global_load_dwordx4 v[108:111], v[40:41], off
	global_load_dwordx4 v[112:115], v[40:41], off offset:16
	global_load_dwordx4 v[116:119], v[42:43], off offset:176
	global_load_dwordx4 v[120:123], v[42:43], off offset:160
	global_load_dwordx4 v[124:127], v[42:43], off offset:144
	global_load_dwordx4 v[128:131], v[42:43], off offset:128
	global_load_dwordx4 v[132:135], v[38:39], off offset:64
	global_load_dwordx4 v[136:139], v[38:39], off offset:80
	global_load_dwordx4 v[140:143], v[40:41], off offset:64
	global_load_dwordx4 v[150:153], v[40:41], off offset:80
	s_add_i32 s12, s0, s17
	s_ashr_i32 s13, s12, 8
	s_cmpk_gt_u32 s12, 0xff
	s_cselect_b64 s[0:1], -1, 0
	s_cmp_lg_u32 s13, 2
	s_cselect_b64 s[2:3], -1, 0
	s_and_b64 s[2:3], s[0:1], s[2:3]
	s_add_i32 s0, s13, -7
	s_cmp_lt_u32 s0, 3
	s_cselect_b64 s[0:1], -1, 0
	s_cmp_eq_u32 s13, 11
	s_cselect_b64 s[10:11], -1, 0
	s_and_b32 s14, s12, 0xffffffc0
	s_cmp_eq_u32 s13, 2
	s_waitcnt vmcnt(15)
	v_cvt_pk_bf16_f32 v54, v84, v85
	v_cvt_pk_bf16_f32 v55, v86, v87
	s_waitcnt vmcnt(12)
	v_cvt_pk_bf16_f32 v18, v96, v97
	v_cvt_pk_bf16_f32 v19, v98, v99
	v_cvt_pk_bf16_f32 v20, v92, v93
	v_cvt_pk_bf16_f32 v21, v94, v95
	v_cvt_pk_bf16_f32 v52, v88, v89
	v_cvt_pk_bf16_f32 v53, v90, v91
	s_waitcnt vmcnt(11)
	v_mfma_f32_32x32x16_bf16 v[2:17], v[18:21], v[100:103], 0
	s_waitcnt vmcnt(10)
	v_mfma_f32_32x32x16_bf16 v[2:17], v[52:55], v[104:107], v[2:17]
	s_waitcnt vmcnt(9)
	v_mfma_f32_32x32x16_bf16 v[18:33], v[18:21], v[108:111], 0
	s_waitcnt vmcnt(8)
	v_mfma_f32_32x32x16_bf16 v[18:33], v[52:55], v[112:115], v[18:33]
	s_waitcnt vmcnt(6)
	v_cvt_pk_bf16_f32 v56, v120, v121
	v_cvt_pk_bf16_f32 v57, v122, v123
	s_waitcnt vmcnt(4)
	v_cvt_pk_bf16_f32 v64, v128, v129
	v_cvt_pk_bf16_f32 v65, v130, v131
	v_cvt_pk_bf16_f32 v66, v124, v125
	v_cvt_pk_bf16_f32 v67, v126, v127
	v_cvt_pk_bf16_f32 v58, v116, v117
	v_cvt_pk_bf16_f32 v59, v118, v119
	s_waitcnt vmcnt(3)
	v_mfma_f32_32x32x16_bf16 v[2:17], v[64:67], v[132:135], v[2:17]
	s_waitcnt vmcnt(1)
	v_mfma_f32_32x32x16_bf16 v[18:33], v[64:67], v[140:143], v[18:33]
	v_mfma_f32_32x32x16_bf16 v[2:17], v[56:59], v[136:139], v[2:17]
	s_waitcnt vmcnt(0)
	v_mfma_f32_32x32x16_bf16 v[18:33], v[56:59], v[150:153], v[18:33]
	global_load_dwordx4 v[84:87], v[42:43], off offset:304
	global_load_dwordx4 v[88:91], v[42:43], off offset:288
	global_load_dwordx4 v[92:95], v[42:43], off offset:272
	global_load_dwordx4 v[96:99], v[42:43], off offset:256
	global_load_dwordx4 v[100:103], v[38:39], off offset:128
	global_load_dwordx4 v[104:107], v[38:39], off offset:144
	global_load_dwordx4 v[108:111], v[40:41], off offset:128
	global_load_dwordx4 v[112:115], v[40:41], off offset:144
	global_load_dwordx4 v[116:119], v[42:43], off offset:432
	global_load_dwordx4 v[120:123], v[42:43], off offset:416
	global_load_dwordx4 v[124:127], v[42:43], off offset:400
	global_load_dwordx4 v[128:131], v[42:43], off offset:384
	global_load_dwordx4 v[132:135], v[38:39], off offset:192
	global_load_dwordx4 v[136:139], v[38:39], off offset:208
	global_load_dwordx4 v[140:143], v[40:41], off offset:192
	global_load_dwordx4 v[150:153], v[40:41], off offset:208
	s_waitcnt vmcnt(14)
	v_cvt_pk_bf16_f32 v56, v88, v89
	v_cvt_pk_bf16_f32 v57, v90, v91
	s_waitcnt vmcnt(12)
	v_cvt_pk_bf16_f32 v64, v96, v97
	v_cvt_pk_bf16_f32 v65, v98, v99
	v_cvt_pk_bf16_f32 v66, v92, v93
	v_cvt_pk_bf16_f32 v67, v94, v95
	v_cvt_pk_bf16_f32 v58, v84, v85
	v_cvt_pk_bf16_f32 v59, v86, v87
	s_waitcnt vmcnt(11)
	v_mfma_f32_32x32x16_bf16 v[2:17], v[64:67], v[100:103], v[2:17]
	s_waitcnt vmcnt(9)
	v_mfma_f32_32x32x16_bf16 v[18:33], v[64:67], v[108:111], v[18:33]
	v_mfma_f32_32x32x16_bf16 v[2:17], v[56:59], v[104:107], v[2:17]
	s_waitcnt vmcnt(8)
	v_mfma_f32_32x32x16_bf16 v[18:33], v[56:59], v[112:115], v[18:33]
	s_waitcnt vmcnt(6)
	v_cvt_pk_bf16_f32 v56, v120, v121
	v_cvt_pk_bf16_f32 v57, v122, v123
	s_waitcnt vmcnt(4)
	v_cvt_pk_bf16_f32 v64, v128, v129
	v_cvt_pk_bf16_f32 v65, v130, v131
	v_cvt_pk_bf16_f32 v66, v124, v125
	v_cvt_pk_bf16_f32 v67, v126, v127
	v_cvt_pk_bf16_f32 v58, v116, v117
	v_cvt_pk_bf16_f32 v59, v118, v119
	s_waitcnt vmcnt(3)
	v_mfma_f32_32x32x16_bf16 v[2:17], v[64:67], v[132:135], v[2:17]
	s_waitcnt vmcnt(1)
	v_mfma_f32_32x32x16_bf16 v[18:33], v[64:67], v[140:143], v[18:33]
	v_mfma_f32_32x32x16_bf16 v[2:17], v[56:59], v[136:139], v[2:17]
	s_waitcnt vmcnt(0)
	v_mfma_f32_32x32x16_bf16 v[18:33], v[56:59], v[150:153], v[18:33]
	s_nop 9
	ds_write2st64_b32 v50, v2, v3 offset1:1
	s_nop 0
	ds_write2st64_b32 v50, v18, v19 offset0:16 offset1:17
	ds_write2st64_b32 v50, v4, v5 offset0:2 offset1:3
	ds_write2st64_b32 v50, v20, v21 offset0:18 offset1:19
	ds_write2st64_b32 v50, v6, v7 offset0:4 offset1:5
	ds_write2st64_b32 v50, v22, v23 offset0:20 offset1:21
	ds_write2st64_b32 v50, v8, v9 offset0:6 offset1:7
	ds_write2st64_b32 v50, v24, v25 offset0:22 offset1:23
	ds_write2st64_b32 v50, v10, v11 offset0:8 offset1:9
	ds_write2st64_b32 v50, v26, v27 offset0:24 offset1:25
	ds_write2st64_b32 v50, v12, v13 offset0:10 offset1:11
	ds_write2st64_b32 v50, v28, v29 offset0:26 offset1:27
	ds_write2st64_b32 v50, v14, v15 offset0:12 offset1:13
	ds_write2st64_b32 v50, v30, v31 offset0:28 offset1:29
	ds_write2st64_b32 v50, v16, v17 offset0:14 offset1:15
	ds_write2st64_b32 v50, v32, v33 offset0:30 offset1:31
	v_or_b32_e32 v2, s12, v44
	v_lshrrev_b32_e32 v4, 1, v2
	v_and_b32_e32 v5, 28, v4
	v_or_b32_e32 v6, v5, v46
	v_add_u32_e32 v5, v48, v5
	s_waitcnt lgkmcnt(0)
	s_barrier
; __device__ __forceinline__ int crow(int r, int hi) { return (r & 3) + 8 * (r >> 2) + 4 * hi; }
; __device__ __forceinline__ int crow(int r, int hi) { return (r & 3) + 8 * (r >> 2) + 4 * hi; }
; __device__ __forceinline__ int crow(int r, int hi) { return (r & 3) + 8 * (r >> 2) + 4 * hi; }
; __device__ __forceinline__ int crow(int r, int hi) { return (r & 3) + 8 * (r >> 2) + 4 * hi; }
;     __device__ __forceinline__ void el(int row, int col, float v) const { if (col < nvalid) { if (act == 1) { v = v > 0.f ? v : 0.f; v = v * v; } C[(size_t)row * ldc + col] = v; } }
;     ...
; #pragma unroll
;         for (int q = 0; q < 4; ++q) { const int rr = 4 * wave + q; float v = 0.f;
; #pragma unroll
;             for (int w = 0; w < 8; ++w) v += red[w * 2048 + rr * 64 + lane];
;             E.el(row0 + crow(rr & 15, hh), col0 + (rr >> 4) * 32 + r32, v, r32); }
	v_cndmask_b32_e64 v5, v5, v6, s[6:7]
	ds_read2st64_b32 v[12:13], v51 offset1:32
	ds_read2st64_b32 v[10:11], v51 offset0:64 offset1:96
	ds_read2st64_b32 v[8:9], v51 offset0:128 offset1:160
	ds_read2st64_b32 v[6:7], v51 offset0:192 offset1:224
	v_add_u32_e32 v3, s12, v47
	s_cselect_b32 s12, 0x80, 0
	v_and_b32_e32 v4, 0x7c, v4
	v_cmp_gt_i32_e64 s[8:9], s21, v2
	v_add_u32_e32 v18, s14, v5
	v_add3_u32 v16, v49, v4, s12
	v_or3_b32 v17, v4, v46, s12
	v_mov_b32_e32 v14, v2
	s_and_saveexec_b64 s[12:13], s[8:9]
	s_cbranch_execz .LBB0_462
	s_mov_b64 s[14:15], -1
	s_and_b64 vcc, exec, s[2:3]
	s_cbranch_vccz .LBB0_460
	v_cndmask_b32_e64 v4, v2, v3, s[10:11]
	v_cndmask_b32_e64 v14, v4, v18, s[0:1]
	s_mov_b64 s[14:15], 0

; __device__ __forceinline__ int crow(int r, int hi) { return (r & 3) + 8 * (r >> 2) + 4 * hi; }
; __device__ __forceinline__ int crow(int r, int hi) { return (r & 3) + 8 * (r >> 2) + 4 * hi; }
;     ...
;     for (int it = (int)blockIdx.x - wg_lo; it < NIT; it += wg_n) { const int ks = it / nT, it2 = it % nT, mb = it2 % nMb, nbk = it2 / nMb, row0 = 32 * mb, col0 = 64 * nbk, kbeg = (ks * 8 + wave) * KW;
;         f32x16 acc0 = {}, acc1 = {};
;         const bf16* b0p = Bt + (size_t)(col0 + r32) * K + 16 * hh + kbeg; const bf16* b1p = b0p + (size_t)32 * K; const float* af = (const float*)Av + (size_t)(row0 + r32) * lda + 16 * hh + kbeg; const bf16* ab = (const bf16*)Av + (size_t)(row0 + r32) * lda + 16 * hh + kbeg;
; #pragma unroll
;         for (int k0 = 0; k0 < KW; k0 += 32) { bf16x8 a0, a1;
;           if (ABF) { a0 = *(const bf16x8*)(ab + k0); a1 = *(const bf16x8*)(ab + k0 + 8); } else {
;             const f32x4 x0 = *(const f32x4*)(af + k0), x1 = *(const f32x4*)(af + k0 + 4), x2 = *(const f32x4*)(af + k0 + 8), x3 = *(const f32x4*)(af + k0 + 12);
;             const u32x4_t p0 = {cvtpk(x0[0], x0[1]), cvtpk(x0[2], x0[3]), cvtpk(x1[0], x1[1]), cvtpk(x1[2], x1[3])}, p1 = {cvtpk(x2[0], x2[1]), cvtpk(x2[2], x2[3]), cvtpk(x3[0], x3[1]), cvtpk(x3[2], x3[3])};
;             a0 = __builtin_bit_cast(bf16x8, p0); a1 = __builtin_bit_cast(bf16x8, p1); }
;             const bf16x8 b00 = *(const bf16x8*)(b0p + k0), b01 = *(const bf16x8*)(b0p + k0 + 8), b10 = *(const bf16x8*)(b1p + k0), b11 = *(const bf16x8*)(b1p + k0 + 8);
;             acc0 = __builtin_amdgcn_mfma_f32_32x32x16_bf16(a0, b00, acc0, 0, 0, 0); acc0 = __builtin_amdgcn_mfma_f32_32x32x16_bf16(a1, b01, acc0, 0, 0, 0);
;             acc1 = __builtin_amdgcn_mfma_f32_32x32x16_bf16(a0, b10, acc1, 0, 0, 0); acc1 = __builtin_amdgcn_mfma_f32_32x32x16_bf16(a1, b11, acc1, 0, 0, 0); }
; #pragma unroll
;         for (int rg = 0; rg < 16; ++rg) { red[wave * 2048 + rg * 64 + lane] = acc0[rg]; red[wave * 2048 + (16 + rg) * 64 + lane] = acc1[rg]; }
;         __syncthreads();
; #pragma unroll
;         for (int q = 0; q < 4; ++q) { const int rr = 4 * wave + q; float v = 0.f;
; #pragma unroll
;             for (int w = 0; w < 8; ++w) v += red[w * 2048 + rr * 64 + lane];
;             E.el(row0 + crow(rr & 15, hh), col0 + (rr >> 4) * 32 + r32, v, r32); }
.LBB0_1339:
	s_ashr_i32 s2, s7, 31
	s_lshr_b32 s2, s2, 25
	s_add_i32 s3, s7, s2
	s_and_b32 s2, s3, 0xff80
	s_sub_i32 s2, s7, s2
	s_bfe_i32 s8, s2, 0x80000
	s_bfe_u32 s8, s8, 0x3000c
	s_add_i32 s8, s2, s8
	s_bfe_i32 s9, s8, 0x80000
	s_and_b32 s8, s8, 0xf8
	s_sub_i32 s2, s2, s8
	s_sext_i32_i16 s9, s9
	s_sext_i32_i8 s2, s2
	s_lshl_b32 s8, s2, 5
	s_lshl_b32 s2, s9, 3
	s_andn2_b32 s2, s2, 63
	s_lshl_b32 s3, s3, 3
	v_or_b32_e32 v2, s2, v44
	s_and_b32 s3, s3, 0xfffffc00
	v_ashrrev_i32_e32 v3, 31, v2
	s_add_i32 s10, s3, s6
	v_lshlrev_b64 v[2:3], 11, v[2:3]
	v_lshl_add_u64 v[2:3], v[34:35], 0, v[2:3]
	s_ashr_i32 s11, s10, 31
	v_lshl_add_u64 v[38:39], s[10:11], 1, v[2:3]
	v_or_b32_e32 v2, s8, v44
	v_ashrrev_i32_e32 v3, 31, v2
	v_lshlrev_b64 v[2:3], 12, v[2:3]
	v_lshl_add_u64 v[2:3], v[36:37], 0, v[2:3]
	v_lshl_add_u64 v[42:43], s[10:11], 2, v[2:3]
	global_load_dwordx4 v[84:87], v[42:43], off offset:48
	global_load_dwordx4 v[88:91], v[42:43], off offset:32
	global_load_dwordx4 v[92:95], v[42:43], off offset:16
	global_load_dwordx4 v[96:99], v[42:43], off
	v_add_co_u32_e32 v40, vcc, s16, v38
	s_nop 1
	global_load_dwordx4 v[100:103], v[38:39], off
	global_load_dwordx4 v[104:107], v[38:39], off offset:16
	v_addc_co_u32_e32 v41, vcc, 0, v39, vcc
	global_load_dwordx4 v[108:111], v[40:41], off
	global_load_dwordx4 v[112:115], v[40:41], off offset:16
	global_load_dwordx4 v[116:119], v[42:43], off offset:176
	global_load_dwordx4 v[120:123], v[42:43], off offset:160
	global_load_dwordx4 v[124:127], v[42:43], off offset:144
	global_load_dwordx4 v[128:131], v[42:43], off offset:128
	global_load_dwordx4 v[132:135], v[38:39], off offset:64
	global_load_dwordx4 v[136:139], v[38:39], off offset:80
	global_load_dwordx4 v[140:143], v[40:41], off offset:64
	global_load_dwordx4 v[150:153], v[40:41], off offset:80
	s_waitcnt vmcnt(15)
	v_cvt_pk_bf16_f32 v52, v84, v85
	v_cvt_pk_bf16_f32 v53, v86, v87
	s_waitcnt vmcnt(12)
	v_cvt_pk_bf16_f32 v18, v96, v97
	v_cvt_pk_bf16_f32 v19, v98, v99
	v_cvt_pk_bf16_f32 v20, v92, v93
	v_cvt_pk_bf16_f32 v21, v94, v95
	v_cvt_pk_bf16_f32 v50, v88, v89
	v_cvt_pk_bf16_f32 v51, v90, v91
	s_waitcnt vmcnt(11)
	v_mfma_f32_32x32x16_bf16 v[2:17], v[18:21], v[100:103], 0
	s_waitcnt vmcnt(10)
	v_mfma_f32_32x32x16_bf16 v[2:17], v[50:53], v[104:107], v[2:17]
	s_waitcnt vmcnt(9)
	v_mfma_f32_32x32x16_bf16 v[18:33], v[18:21], v[108:111], 0
	s_waitcnt vmcnt(8)
	v_mfma_f32_32x32x16_bf16 v[18:33], v[50:53], v[112:115], v[18:33]
	s_waitcnt vmcnt(6)
	v_cvt_pk_bf16_f32 v54, v120, v121
	v_cvt_pk_bf16_f32 v55, v122, v123
	s_waitcnt vmcnt(4)
	v_cvt_pk_bf16_f32 v62, v128, v129
	v_cvt_pk_bf16_f32 v63, v130, v131
	v_cvt_pk_bf16_f32 v64, v124, v125
	v_cvt_pk_bf16_f32 v65, v126, v127
	v_cvt_pk_bf16_f32 v56, v116, v117
	v_cvt_pk_bf16_f32 v57, v118, v119
	s_waitcnt vmcnt(3)
	v_mfma_f32_32x32x16_bf16 v[2:17], v[62:65], v[132:135], v[2:17]
	s_waitcnt vmcnt(1)
	v_mfma_f32_32x32x16_bf16 v[18:33], v[62:65], v[140:143], v[18:33]
	v_mfma_f32_32x32x16_bf16 v[2:17], v[54:57], v[136:139], v[2:17]
	s_waitcnt vmcnt(0)
	v_mfma_f32_32x32x16_bf16 v[18:33], v[54:57], v[150:153], v[18:33]
	global_load_dwordx4 v[84:87], v[42:43], off offset:304
	global_load_dwordx4 v[88:91], v[42:43], off offset:288
	global_load_dwordx4 v[92:95], v[42:43], off offset:272
	global_load_dwordx4 v[96:99], v[42:43], off offset:256
	global_load_dwordx4 v[100:103], v[38:39], off offset:128
	global_load_dwordx4 v[104:107], v[38:39], off offset:144
	global_load_dwordx4 v[108:111], v[40:41], off offset:128
	global_load_dwordx4 v[112:115], v[40:41], off offset:144
	global_load_dwordx4 v[116:119], v[42:43], off offset:432
	global_load_dwordx4 v[120:123], v[42:43], off offset:416
	global_load_dwordx4 v[124:127], v[42:43], off offset:400
	global_load_dwordx4 v[128:131], v[42:43], off offset:384
	global_load_dwordx4 v[132:135], v[38:39], off offset:192
	global_load_dwordx4 v[136:139], v[38:39], off offset:208
	global_load_dwordx4 v[140:143], v[40:41], off offset:192
	global_load_dwordx4 v[150:153], v[40:41], off offset:208
	s_waitcnt vmcnt(14)
	v_cvt_pk_bf16_f32 v54, v88, v89
	v_cvt_pk_bf16_f32 v55, v90, v91
	s_waitcnt vmcnt(12)
	v_cvt_pk_bf16_f32 v62, v96, v97
	v_cvt_pk_bf16_f32 v63, v98, v99
	v_cvt_pk_bf16_f32 v64, v92, v93
	v_cvt_pk_bf16_f32 v65, v94, v95
	v_cvt_pk_bf16_f32 v56, v84, v85
	v_cvt_pk_bf16_f32 v57, v86, v87
	s_waitcnt vmcnt(11)
	v_mfma_f32_32x32x16_bf16 v[2:17], v[62:65], v[100:103], v[2:17]
	s_waitcnt vmcnt(9)
	v_mfma_f32_32x32x16_bf16 v[18:33], v[62:65], v[108:111], v[18:33]
	v_mfma_f32_32x32x16_bf16 v[2:17], v[54:57], v[104:107], v[2:17]
	s_waitcnt vmcnt(8)
	v_mfma_f32_32x32x16_bf16 v[18:33], v[54:57], v[112:115], v[18:33]
	s_waitcnt vmcnt(6)
	v_cvt_pk_bf16_f32 v54, v120, v121
	v_cvt_pk_bf16_f32 v55, v122, v123
	s_waitcnt vmcnt(4)
	v_cvt_pk_bf16_f32 v62, v128, v129
	v_cvt_pk_bf16_f32 v63, v130, v131
	v_cvt_pk_bf16_f32 v64, v124, v125
	v_cvt_pk_bf16_f32 v65, v126, v127
	v_cvt_pk_bf16_f32 v56, v116, v117
	v_cvt_pk_bf16_f32 v57, v118, v119
	s_waitcnt vmcnt(3)
	v_mfma_f32_32x32x16_bf16 v[2:17], v[62:65], v[132:135], v[2:17]
	s_waitcnt vmcnt(1)
	v_mfma_f32_32x32x16_bf16 v[18:33], v[62:65], v[140:143], v[18:33]
	v_mfma_f32_32x32x16_bf16 v[2:17], v[54:57], v[136:139], v[2:17]
	s_waitcnt vmcnt(0)
	v_mfma_f32_32x32x16_bf16 v[18:33], v[54:57], v[150:153], v[18:33]
	s_nop 9
	ds_write2st64_b32 v46, v2, v3 offset1:1
	s_nop 0
	ds_write2st64_b32 v46, v18, v19 offset0:16 offset1:17
	ds_write2st64_b32 v46, v4, v5 offset0:2 offset1:3
	ds_write2st64_b32 v46, v20, v21 offset0:18 offset1:19
	ds_write2st64_b32 v46, v6, v7 offset0:4 offset1:5
	ds_write2st64_b32 v46, v22, v23 offset0:20 offset1:21
	ds_write2st64_b32 v46, v8, v9 offset0:6 offset1:7
	ds_write2st64_b32 v46, v24, v25 offset0:22 offset1:23
	ds_write2st64_b32 v46, v10, v11 offset0:8 offset1:9
	ds_write2st64_b32 v46, v26, v27 offset0:24 offset1:25
	ds_write2st64_b32 v46, v12, v13 offset0:10 offset1:11
	ds_write2st64_b32 v46, v28, v29 offset0:26 offset1:27
	ds_write2st64_b32 v46, v14, v15 offset0:12 offset1:13
	ds_write2st64_b32 v46, v30, v31 offset0:28 offset1:29
	ds_write2st64_b32 v46, v16, v17 offset0:14 offset1:15
	ds_write2st64_b32 v46, v32, v33 offset0:30 offset1:31
	v_add_u32_e32 v4, s2, v47
	s_movk_i32 s2, 0x400
	v_cmp_gt_i32_e32 vcc, s2, v4
	s_waitcnt lgkmcnt(0)
	s_barrier
; __device__ __forceinline__ int crow(int r, int hi) { return (r & 3) + 8 * (r >> 2) + 4 * hi; }
; __device__ __forceinline__ int crow(int r, int hi) { return (r & 3) + 8 * (r >> 2) + 4 * hi; }
; __device__ __forceinline__ int crow(int r, int hi) { return (r & 3) + 8 * (r >> 2) + 4 * hi; }
; __device__ __forceinline__ int crow(int r, int hi) { return (r & 3) + 8 * (r >> 2) + 4 * hi; }
;     __device__ __forceinline__ void el(int row, int col, float v) const { if (col < nvalid) { if (act == 1) { v = v > 0.f ? v : 0.f; v = v * v; } C[(size_t)row * ldc + col] = v; } }
;     ...
; #pragma unroll
;         for (int q = 0; q < 4; ++q) { const int rr = 4 * wave + q; float v = 0.f;
; #pragma unroll
;             for (int w = 0; w < 8; ++w) v += red[w * 2048 + rr * 64 + lane];
;             E.el(row0 + crow(rr & 15, hh), col0 + (rr >> 4) * 32 + r32, v, r32); }
	s_and_saveexec_b64 s[2:3], vcc
	s_cbranch_execz .LBB0_1338
	ds_read2st64_b32 v[6:7], v48 offset1:1
	ds_read2st64_b32 v[8:9], v48 offset0:32 offset1:33
	ds_read2st64_b32 v[10:11], v48 offset0:64 offset1:65
	ds_read2st64_b32 v[12:13], v48 offset0:96 offset1:97
	ds_read2st64_b32 v[14:15], v48 offset0:128 offset1:129
	ds_read2st64_b32 v[16:17], v48 offset0:160 offset1:161
	ds_read2st64_b32 v[18:19], v48 offset0:192 offset1:193
	ds_read2st64_b32 v[20:21], v48 offset0:224 offset1:225
	s_waitcnt lgkmcnt(7)
	v_add_f32_e32 v3, 0, v6
	s_waitcnt lgkmcnt(6)
	v_add_f32_e32 v3, v3, v8
	s_waitcnt lgkmcnt(5)
	v_add_f32_e32 v3, v3, v10
	s_waitcnt lgkmcnt(4)
	v_add_f32_e32 v3, v3, v12
	s_waitcnt lgkmcnt(3)
	v_add_f32_e32 v3, v3, v14
	s_waitcnt lgkmcnt(2)
	v_add_f32_e32 v3, v3, v16
	v_or_b32_e32 v2, s8, v45
	s_waitcnt lgkmcnt(1)
	v_add_f32_e32 v3, v3, v18
	s_waitcnt lgkmcnt(0)
	v_add_f32_e32 v6, v3, v20
	v_ashrrev_i32_e32 v3, 31, v2
	v_ashrrev_i32_e32 v5, 31, v4
	v_lshlrev_b64 v[22:23], 12, v[2:3]
	v_add_f32_e32 v3, 0, v7
	v_lshl_add_u64 v[22:23], s[0:1], 0, v[22:23]
	v_lshlrev_b64 v[4:5], 2, v[4:5]
	v_add_f32_e32 v3, v3, v9
	v_lshl_add_u64 v[22:23], v[22:23], 0, v[4:5]
	v_add_f32_e32 v3, v3, v11
	global_store_dword v[22:23], v6, off
	v_or_b32_e32 v6, 1, v2
	v_add_f32_e32 v3, v3, v13
	v_add_f32_e32 v3, v3, v15
	v_ashrrev_i32_e32 v7, 31, v6
	v_add_f32_e32 v3, v3, v17
	v_lshlrev_b64 v[6:7], 12, v[6:7]
	v_add_f32_e32 v3, v3, v19
	v_lshl_add_u64 v[6:7], s[0:1], 0, v[6:7]
	v_add_f32_e32 v3, v3, v21
	v_lshl_add_u64 v[6:7], v[6:7], 0, v[4:5]
	global_store_dword v[6:7], v3, off
	ds_read2st64_b32 v[6:7], v48 offset0:2 offset1:3
	ds_read2st64_b32 v[10:11], v48 offset0:34 offset1:35
	ds_read2st64_b32 v[12:13], v48 offset0:66 offset1:67
	ds_read2st64_b32 v[14:15], v48 offset0:98 offset1:99
	ds_read2st64_b32 v[16:17], v48 offset0:130 offset1:131
	ds_read2st64_b32 v[18:19], v48 offset0:162 offset1:163
	ds_read2st64_b32 v[20:21], v48 offset0:194 offset1:195
	ds_read2st64_b32 v[22:23], v48 offset0:226 offset1:227
	s_waitcnt lgkmcnt(7)
	v_add_f32_e32 v3, 0, v6
	s_waitcnt lgkmcnt(6)
	v_add_f32_e32 v3, v3, v10
	s_waitcnt lgkmcnt(5)
	v_add_f32_e32 v3, v3, v12
	v_or_b32_e32 v8, 2, v2
	s_waitcnt lgkmcnt(4)
	v_add_f32_e32 v3, v3, v14
	s_waitcnt lgkmcnt(3)
	v_add_f32_e32 v3, v3, v16
	v_ashrrev_i32_e32 v9, 31, v8
	s_waitcnt lgkmcnt(2)
	v_add_f32_e32 v3, v3, v18
	v_lshlrev_b64 v[8:9], 12, v[8:9]
	s_waitcnt lgkmcnt(1)
	v_add_f32_e32 v3, v3, v20
	v_lshl_add_u64 v[8:9], s[0:1], 0, v[8:9]
	s_waitcnt lgkmcnt(0)
	v_add_f32_e32 v3, v3, v22
	v_lshl_add_u64 v[8:9], v[8:9], 0, v[4:5]
	global_store_dword v[8:9], v3, off
	v_add_f32_e32 v3, 0, v7
	v_add_f32_e32 v3, v3, v11
	v_add_f32_e32 v3, v3, v13
	v_add_f32_e32 v3, v3, v15
	v_add_f32_e32 v3, v3, v17
	v_add_f32_e32 v3, v3, v19
	v_or_b32_e32 v2, 3, v2
	v_add_f32_e32 v3, v3, v21
	v_add_f32_e32 v6, v3, v23
	v_ashrrev_i32_e32 v3, 31, v2
	v_lshlrev_b64 v[2:3], 12, v[2:3]
	v_lshl_add_u64 v[2:3], s[0:1], 0, v[2:3]
	v_lshl_add_u64 v[2:3], v[2:3], 0, v[4:5]
	global_store_dword v[2:3], v6, off
	s_branch .LBB0_1338

; __device__ __forceinline__ int crow(int r, int hi) { return (r & 3) + 8 * (r >> 2) + 4 * hi; }
; __device__ __forceinline__ int crow(int r, int hi) { return (r & 3) + 8 * (r >> 2) + 4 * hi; }
;     ...
;     for (int it = (int)blockIdx.x - wg_lo; it < NIT; it += wg_n) { const int ks = it / nT, it2 = it % nT, mb = it2 % nMb, nbk = it2 / nMb, row0 = 32 * mb, col0 = 64 * nbk, kbeg = (ks * 8 + wave) * KW;
;         f32x16 acc0 = {}, acc1 = {};
;         const bf16* b0p = Bt + (size_t)(col0 + r32) * K + 16 * hh + kbeg; const bf16* b1p = b0p + (size_t)32 * K; const float* af = (const float*)Av + (size_t)(row0 + r32) * lda + 16 * hh + kbeg; const bf16* ab = (const bf16*)Av + (size_t)(row0 + r32) * lda + 16 * hh + kbeg;
; #pragma unroll
;         for (int k0 = 0; k0 < KW; k0 += 32) { bf16x8 a0, a1;
;           if (ABF) { a0 = *(const bf16x8*)(ab + k0); a1 = *(const bf16x8*)(ab + k0 + 8); } else {
;             const f32x4 x0 = *(const f32x4*)(af + k0), x1 = *(const f32x4*)(af + k0 + 4), x2 = *(const f32x4*)(af + k0 + 8), x3 = *(const f32x4*)(af + k0 + 12);
;             const u32x4_t p0 = {cvtpk(x0[0], x0[1]), cvtpk(x0[2], x0[3]), cvtpk(x1[0], x1[1]), cvtpk(x1[2], x1[3])}, p1 = {cvtpk(x2[0], x2[1]), cvtpk(x2[2], x2[3]), cvtpk(x3[0], x3[1]), cvtpk(x3[2], x3[3])};
;             a0 = __builtin_bit_cast(bf16x8, p0); a1 = __builtin_bit_cast(bf16x8, p1); }
;             const bf16x8 b00 = *(const bf16x8*)(b0p + k0), b01 = *(const bf16x8*)(b0p + k0 + 8), b10 = *(const bf16x8*)(b1p + k0), b11 = *(const bf16x8*)(b1p + k0 + 8);
;             acc0 = __builtin_amdgcn_mfma_f32_32x32x16_bf16(a0, b00, acc0, 0, 0, 0); acc0 = __builtin_amdgcn_mfma_f32_32x32x16_bf16(a1, b01, acc0, 0, 0, 0);
;             acc1 = __builtin_amdgcn_mfma_f32_32x32x16_bf16(a0, b10, acc1, 0, 0, 0); acc1 = __builtin_amdgcn_mfma_f32_32x32x16_bf16(a1, b11, acc1, 0, 0, 0); }
; #pragma unroll
;         for (int rg = 0; rg < 16; ++rg) { red[wave * 2048 + rg * 64 + lane] = acc0[rg]; red[wave * 2048 + (16 + rg) * 64 + lane] = acc1[rg]; }
;         __syncthreads();
; #pragma unroll
;         for (int q = 0; q < 4; ++q) { const int rr = 4 * wave + q; float v = 0.f;
; #pragma unroll
;             for (int w = 0; w < 8; ++w) v += red[w * 2048 + rr * 64 + lane];
;             E.el(row0 + crow(rr & 15, hh), col0 + (rr >> 4) * 32 + r32, v, r32); }
.LBB0_1415:
	s_ashr_i32 s11, s10, 31
	s_lshr_b32 s11, s11, 24
	s_add_i32 s27, s10, s11
	s_and_b32 s11, s27, 0xff00
	s_sub_i32 s11, s10, s11
	s_sext_i32_i16 s26, s11
	s_bfe_u32 s26, s26, 0x5001a
	s_add_i32 s26, s11, s26
	s_sext_i32_i16 s28, s26
	s_lshl_b32 s28, s28, 1
	s_and_b32 s30, s28, 0xffffffc0
	s_and_b32 s26, s26, 0xffe0
	s_lshl_b32 s27, s27, 2
	v_or_b32_e32 v2, s30, v39
	s_sub_i32 s11, s11, s26
	s_and_b32 s27, s27, 0xfffffc00
	v_ashrrev_i32_e32 v3, 31, v2
	s_sext_i32_i16 s26, s11
	s_add_i32 s28, s27, s8
	v_lshlrev_b64 v[2:3], 11, v[2:3]
	s_lshl_b32 s11, s26, 5
	v_lshl_add_u64 v[2:3], v[34:35], 0, v[2:3]
	s_ashr_i32 s29, s28, 31
	v_lshl_add_u64 v[72:73], s[28:29], 1, v[2:3]
	v_or_b32_e32 v2, s11, v39
	v_ashrrev_i32_e32 v3, 31, v2
	v_lshlrev_b64 v[2:3], 12, v[2:3]
	v_lshl_add_u64 v[2:3], v[36:37], 0, v[2:3]
	v_lshl_add_u64 v[74:75], s[28:29], 2, v[2:3]
	global_load_dwordx4 v[84:87], v[74:75], off offset:48
	global_load_dwordx4 v[88:91], v[74:75], off offset:32
	global_load_dwordx4 v[92:95], v[74:75], off offset:16
	global_load_dwordx4 v[96:99], v[74:75], off
	v_add_co_u32_e32 v76, vcc, s34, v72
	s_nop 1
	v_addc_co_u32_e32 v77, vcc, 0, v73, vcc
	global_load_dwordx4 v[100:103], v[72:73], off
	global_load_dwordx4 v[104:107], v[72:73], off offset:16
	global_load_dwordx4 v[108:111], v[76:77], off
	global_load_dwordx4 v[112:115], v[76:77], off offset:16
	global_load_dwordx4 v[116:119], v[74:75], off offset:176
	global_load_dwordx4 v[120:123], v[74:75], off offset:160
	global_load_dwordx4 v[124:127], v[74:75], off offset:144
	global_load_dwordx4 v[128:131], v[74:75], off offset:128
	global_load_dwordx4 v[132:135], v[72:73], off offset:64
	global_load_dwordx4 v[136:139], v[72:73], off offset:80
	global_load_dwordx4 v[140:143], v[76:77], off offset:64
	global_load_dwordx4 v[150:153], v[76:77], off offset:80
	s_add_i32 s30, s30, s9
	s_ashr_i32 s28, s26, 1
	s_ashr_i32 s27, s30, 7
	s_and_b32 s28, s28, -4
	s_add_i32 s28, s27, s28
	s_ashr_i32 s29, s28, 31
	s_lshl_b64 s[28:29], s[28:29], 6
	s_add_i32 s10, s10, s31
	s_waitcnt vmcnt(15)
	v_cvt_pk_bf16_f32 v50, v84, v85
	v_cvt_pk_bf16_f32 v51, v86, v87
	s_waitcnt vmcnt(12)
	v_cvt_pk_bf16_f32 v18, v96, v97
	v_cvt_pk_bf16_f32 v19, v98, v99
	v_cvt_pk_bf16_f32 v20, v92, v93
	v_cvt_pk_bf16_f32 v21, v94, v95
	v_cvt_pk_bf16_f32 v48, v88, v89
	v_cvt_pk_bf16_f32 v49, v90, v91
	s_waitcnt vmcnt(11)
	v_mfma_f32_32x32x16_bf16 v[2:17], v[18:21], v[100:103], 0
	s_waitcnt vmcnt(10)
	v_mfma_f32_32x32x16_bf16 v[2:17], v[48:51], v[104:107], v[2:17]
	s_waitcnt vmcnt(9)
	v_mfma_f32_32x32x16_bf16 v[18:33], v[18:21], v[108:111], 0
	s_waitcnt vmcnt(8)
	v_mfma_f32_32x32x16_bf16 v[18:33], v[48:51], v[112:115], v[18:33]
	s_waitcnt vmcnt(6)
	v_cvt_pk_bf16_f32 v52, v120, v121
	v_cvt_pk_bf16_f32 v53, v122, v123
	s_waitcnt vmcnt(4)
	v_cvt_pk_bf16_f32 v60, v128, v129
	v_cvt_pk_bf16_f32 v61, v130, v131
	v_cvt_pk_bf16_f32 v62, v124, v125
	v_cvt_pk_bf16_f32 v63, v126, v127
	v_cvt_pk_bf16_f32 v54, v116, v117
	v_cvt_pk_bf16_f32 v55, v118, v119
	s_waitcnt vmcnt(3)
	v_mfma_f32_32x32x16_bf16 v[2:17], v[60:63], v[132:135], v[2:17]
	s_waitcnt vmcnt(1)
	v_mfma_f32_32x32x16_bf16 v[18:33], v[60:63], v[140:143], v[18:33]
	v_mfma_f32_32x32x16_bf16 v[2:17], v[52:55], v[136:139], v[2:17]
	s_waitcnt vmcnt(0)
	v_mfma_f32_32x32x16_bf16 v[18:33], v[52:55], v[150:153], v[18:33]
	global_load_dwordx4 v[84:87], v[74:75], off offset:304
	global_load_dwordx4 v[88:91], v[74:75], off offset:288
	global_load_dwordx4 v[92:95], v[74:75], off offset:272
	global_load_dwordx4 v[96:99], v[74:75], off offset:256
	global_load_dwordx4 v[100:103], v[72:73], off offset:128
	global_load_dwordx4 v[104:107], v[72:73], off offset:144
	global_load_dwordx4 v[108:111], v[76:77], off offset:128
	global_load_dwordx4 v[112:115], v[76:77], off offset:144
	global_load_dwordx4 v[116:119], v[74:75], off offset:432
	global_load_dwordx4 v[120:123], v[74:75], off offset:416
	global_load_dwordx4 v[124:127], v[74:75], off offset:400
	global_load_dwordx4 v[128:131], v[74:75], off offset:384
	global_load_dwordx4 v[132:135], v[72:73], off offset:192
	global_load_dwordx4 v[136:139], v[72:73], off offset:208
	global_load_dwordx4 v[140:143], v[76:77], off offset:192
	global_load_dwordx4 v[150:153], v[76:77], off offset:208
	s_waitcnt vmcnt(14)
	v_cvt_pk_bf16_f32 v52, v88, v89
	v_cvt_pk_bf16_f32 v53, v90, v91
	s_waitcnt vmcnt(12)
	v_cvt_pk_bf16_f32 v60, v96, v97
	v_cvt_pk_bf16_f32 v61, v98, v99
	v_cvt_pk_bf16_f32 v62, v92, v93
	v_cvt_pk_bf16_f32 v63, v94, v95
	v_cvt_pk_bf16_f32 v54, v84, v85
	v_cvt_pk_bf16_f32 v55, v86, v87
	s_waitcnt vmcnt(11)
	v_mfma_f32_32x32x16_bf16 v[2:17], v[60:63], v[100:103], v[2:17]
	s_waitcnt vmcnt(9)
	v_mfma_f32_32x32x16_bf16 v[18:33], v[60:63], v[108:111], v[18:33]
	v_mfma_f32_32x32x16_bf16 v[2:17], v[52:55], v[104:107], v[2:17]
	s_waitcnt vmcnt(8)
	v_mfma_f32_32x32x16_bf16 v[18:33], v[52:55], v[112:115], v[18:33]
	s_waitcnt vmcnt(6)
	v_cvt_pk_bf16_f32 v52, v120, v121
	v_cvt_pk_bf16_f32 v53, v122, v123
	s_waitcnt vmcnt(4)
	v_cvt_pk_bf16_f32 v60, v128, v129
	v_cvt_pk_bf16_f32 v61, v130, v131
	v_cvt_pk_bf16_f32 v62, v124, v125
	v_cvt_pk_bf16_f32 v63, v126, v127
	v_cvt_pk_bf16_f32 v54, v116, v117
	v_cvt_pk_bf16_f32 v55, v118, v119
	s_waitcnt vmcnt(3)
	v_mfma_f32_32x32x16_bf16 v[2:17], v[60:63], v[132:135], v[2:17]
	s_waitcnt vmcnt(1)
	v_mfma_f32_32x32x16_bf16 v[18:33], v[60:63], v[140:143], v[18:33]
	v_mfma_f32_32x32x16_bf16 v[2:17], v[52:55], v[136:139], v[2:17]
	s_waitcnt vmcnt(0)
	v_mfma_f32_32x32x16_bf16 v[18:33], v[52:55], v[150:153], v[18:33]
	s_nop 9
	ds_write2st64_b32 v43, v2, v3 offset1:1
	s_nop 0
	ds_write2st64_b32 v43, v18, v19 offset0:16 offset1:17
	ds_write2st64_b32 v43, v4, v5 offset0:2 offset1:3
	ds_write2st64_b32 v43, v20, v21 offset0:18 offset1:19
	ds_write2st64_b32 v43, v6, v7 offset0:4 offset1:5
	ds_write2st64_b32 v43, v22, v23 offset0:20 offset1:21
	ds_write2st64_b32 v43, v8, v9 offset0:6 offset1:7
	ds_write2st64_b32 v43, v24, v25 offset0:22 offset1:23
	ds_write2st64_b32 v43, v10, v11 offset0:8 offset1:9
	ds_write2st64_b32 v43, v26, v27 offset0:24 offset1:25
	ds_write2st64_b32 v43, v12, v13 offset0:10 offset1:11
	ds_write2st64_b32 v43, v28, v29 offset0:26 offset1:27
	ds_write2st64_b32 v43, v14, v15 offset0:12 offset1:13
	ds_write2st64_b32 v43, v30, v31 offset0:28 offset1:29
	ds_write2st64_b32 v43, v16, v17 offset0:14 offset1:15
	ds_write2st64_b32 v43, v32, v33 offset0:30 offset1:31
	v_or_b32_e32 v2, s30, v39
	v_ashrrev_i32_e32 v3, 31, v2
	v_lshl_add_u64 v[4:5], v[2:3], 2, s[6:7]
	v_bfe_u32 v24, v2, 4, 3
	v_lshlrev_b32_e32 v2, 2, v2
	s_waitcnt lgkmcnt(0)
	s_barrier
; __device__ __forceinline__ int crow(int r, int hi) { return (r & 3) + 8 * (r >> 2) + 4 * hi; }
; __device__ __forceinline__ int crow(int r, int hi) { return (r & 3) + 8 * (r >> 2) + 4 * hi; }
; __device__ __forceinline__ int crow(int r, int hi) { return (r & 3) + 8 * (r >> 2) + 4 * hi; }
; __device__ __forceinline__ int crow(int r, int hi) { return (r & 3) + 8 * (r >> 2) + 4 * hi; }
;     __device__ __forceinline__ void el(int row, int col, float v) const { if (col < nvalid) { if (act == 1) { v = v > 0.f ? v : 0.f; v = v * v; } C[(size_t)row * ldc + col] = v; } }
;     ...
; #pragma unroll
;         for (int q = 0; q < 4; ++q) { const int rr = 4 * wave + q; float v = 0.f;
; #pragma unroll
;             for (int w = 0; w < 8; ++w) v += red[w * 2048 + rr * 64 + lane];
;             E.el(row0 + crow(rr & 15, hh), col0 + (rr >> 4) * 32 + r32, v, r32); }
	v_and_b32_e32 v25, 32, v2
	ds_read2st64_b32 v[2:3], v45 offset1:1
	ds_read2st64_b32 v[6:7], v45 offset0:32 offset1:33
	ds_read2st64_b32 v[8:9], v45 offset0:64 offset1:65
	ds_read2st64_b32 v[10:11], v45 offset0:96 offset1:97
	ds_read2st64_b32 v[12:13], v45 offset0:128 offset1:129
	ds_read2st64_b32 v[14:15], v45 offset0:160 offset1:161
	ds_read2st64_b32 v[16:17], v45 offset0:192 offset1:193
	ds_read2st64_b32 v[18:19], v45 offset0:224 offset1:225
	s_waitcnt lgkmcnt(7)
	v_add_f32_e32 v2, 0, v2
	s_waitcnt lgkmcnt(6)
	v_add_f32_e32 v2, v2, v6
	s_waitcnt lgkmcnt(5)
	v_add_f32_e32 v2, v2, v8
	s_waitcnt lgkmcnt(4)
	v_add_f32_e32 v2, v2, v10
	s_waitcnt lgkmcnt(3)
	v_add_f32_e32 v2, v2, v12
	s_waitcnt lgkmcnt(2)
	v_add_f32_e32 v2, v2, v14
	v_or_b32_e32 v20, s11, v38
	s_waitcnt lgkmcnt(1)
	v_add_f32_e32 v2, v2, v16
	v_ashrrev_i32_e32 v21, 31, v20
	s_waitcnt lgkmcnt(0)
	v_add_f32_e32 v2, v2, v18
	v_lshlrev_b64 v[22:23], 11, v[20:21]
	v_lshl_add_u64 v[22:23], v[4:5], 0, v[22:23]
	v_bfe_u32 v6, v2, 16, 1
	global_store_dword v[22:23], v2, off
	v_add3_u32 v2, v2, v6, s66
	v_lshrrev_b32_e32 v6, 2, v20
	v_and_b32_e32 v6, 56, v6
	v_or3_b32 v20, s28, v6, v24
	v_mov_b32_e32 v21, s29
	v_lshlrev_b64 v[20:21], 6, v[20:21]
	v_or_b32_e32 v6, v20, v38
	v_or_b32_e32 v20, v6, v25
	v_lshl_add_u64 v[20:21], v[20:21], 4, v[40:41]
	global_store_short_d16_hi v[20:21], v2, off
	v_add_f32_e32 v2, 0, v3
	v_add_f32_e32 v2, v2, v7
	v_add_f32_e32 v2, v2, v9
	v_add_f32_e32 v2, v2, v11
	v_add_f32_e32 v2, v2, v13
	v_add_f32_e32 v2, v2, v15
	v_add_f32_e32 v2, v2, v17
	s_bfe_i32 s28, s26, 0x1a0001
	v_add_f32_e32 v6, v2, v19
	v_or_b32_e32 v2, s11, v42
	s_and_b32 s28, s28, -4
	v_ashrrev_i32_e32 v3, 31, v2
	s_add_i32 s28, s28, s27
	v_lshlrev_b64 v[2:3], 11, v[2:3]
	s_ashr_i32 s29, s28, 31
	s_lshl_b32 s26, s26, 3
	v_lshl_add_u64 v[2:3], v[4:5], 0, v[2:3]
	s_lshl_b64 s[28:29], s[28:29], 6
	s_and_b32 s26, s26, 56
	global_store_dword v[2:3], v6, off
	v_bfe_u32 v2, v6, 16, 1
	s_or_b32 s26, s28, s26
	v_add3_u32 v8, v6, v2, s66
	v_or_b32_e32 v2, s26, v24
	v_mov_b32_e32 v3, s29
	v_lshlrev_b64 v[2:3], 6, v[2:3]
	v_or_b32_e32 v6, v2, v42
	v_or_b32_e32 v6, v6, v25
	v_mov_b32_e32 v7, v3
	v_lshl_add_u64 v[6:7], v[6:7], 4, v[40:41]
	global_store_short_d16_hi v[6:7], v8, off
	ds_read2st64_b32 v[6:7], v45 offset0:2 offset1:3
	ds_read2st64_b32 v[8:9], v45 offset0:34 offset1:35
	ds_read2st64_b32 v[10:11], v45 offset0:66 offset1:67
	ds_read2st64_b32 v[12:13], v45 offset0:98 offset1:99
	ds_read2st64_b32 v[14:15], v45 offset0:130 offset1:131
	ds_read2st64_b32 v[16:17], v45 offset0:162 offset1:163
	ds_read2st64_b32 v[18:19], v45 offset0:194 offset1:195
	ds_read2st64_b32 v[20:21], v45 offset0:226 offset1:227
	s_waitcnt lgkmcnt(7)
	v_add_f32_e32 v6, 0, v6
	s_waitcnt lgkmcnt(6)
	v_add_f32_e32 v6, v6, v8
	s_waitcnt lgkmcnt(5)
	v_add_f32_e32 v6, v6, v10
	s_waitcnt lgkmcnt(4)
	v_add_f32_e32 v6, v6, v12
	s_waitcnt lgkmcnt(3)
	v_add_f32_e32 v6, v6, v14
	s_waitcnt lgkmcnt(2)
	v_add_f32_e32 v6, v6, v16
	v_or_b32_e32 v22, s11, v44
	s_waitcnt lgkmcnt(1)
	v_add_f32_e32 v6, v6, v18
	v_ashrrev_i32_e32 v23, 31, v22
	s_waitcnt lgkmcnt(0)
	v_add_f32_e32 v6, v6, v20
	v_lshlrev_b64 v[22:23], 11, v[22:23]
	v_lshl_add_u64 v[22:23], v[4:5], 0, v[22:23]
	v_bfe_u32 v8, v6, 16, 1
	global_store_dword v[22:23], v6, off
	v_add3_u32 v6, v6, v8, s66
	v_or_b32_e32 v8, v2, v44
	v_or_b32_e32 v22, v8, v25
	v_mov_b32_e32 v23, v3
	v_lshl_add_u64 v[22:23], v[22:23], 4, v[40:41]
	global_store_short_d16_hi v[22:23], v6, off
	v_add_f32_e32 v6, 0, v7
	v_add_f32_e32 v6, v6, v9
	v_add_f32_e32 v6, v6, v11
	v_add_f32_e32 v6, v6, v13
	v_add_f32_e32 v6, v6, v15
	v_add_f32_e32 v6, v6, v17
	v_add_f32_e32 v6, v6, v19
	v_add_f32_e32 v8, v6, v21
	v_or_b32_e32 v6, s11, v46
	v_ashrrev_i32_e32 v7, 31, v6
	v_lshlrev_b64 v[6:7], 11, v[6:7]
	v_lshl_add_u64 v[4:5], v[4:5], 0, v[6:7]
	v_or_b32_e32 v2, v2, v46
	global_store_dword v[4:5], v8, off
	v_bfe_u32 v4, v8, 16, 1
	v_or_b32_e32 v2, v2, v25
	v_add3_u32 v4, v8, v4, s66
	v_lshl_add_u64 v[2:3], v[2:3], 4, v[40:41]
	s_cmpk_lt_i32 s10, 0x100
	global_store_short_d16_hi v[2:3], v4, off
	s_barrier
	s_cbranch_scc1 .LBB0_1415

; __device__ __forceinline__ int crow(int r, int hi) { return (r & 3) + 8 * (r >> 2) + 4 * hi; }
; __device__ __forceinline__ int crow(int r, int hi) { return (r & 3) + 8 * (r >> 2) + 4 * hi; }
;     ...
;     for (int it = (int)blockIdx.x - wg_lo; it < NIT; it += wg_n) { const int ks = it / nT, it2 = it % nT, mb = it2 % nMb, nbk = it2 / nMb, row0 = 32 * mb, col0 = 64 * nbk, kbeg = (ks * 8 + wave) * KW;
;         f32x16 acc0 = {}, acc1 = {};
;         const bf16* b0p = Bt + (size_t)(col0 + r32) * K + 16 * hh + kbeg; const bf16* b1p = b0p + (size_t)32 * K; const float* af = (const float*)Av + (size_t)(row0 + r32) * lda + 16 * hh + kbeg; const bf16* ab = (const bf16*)Av + (size_t)(row0 + r32) * lda + 16 * hh + kbeg;
; #pragma unroll
;         for (int k0 = 0; k0 < KW; k0 += 32) { bf16x8 a0, a1;
;           if (ABF) { a0 = *(const bf16x8*)(ab + k0); a1 = *(const bf16x8*)(ab + k0 + 8); } else {
;             const f32x4 x0 = *(const f32x4*)(af + k0), x1 = *(const f32x4*)(af + k0 + 4), x2 = *(const f32x4*)(af + k0 + 8), x3 = *(const f32x4*)(af + k0 + 12);
;             const u32x4_t p0 = {cvtpk(x0[0], x0[1]), cvtpk(x0[2], x0[3]), cvtpk(x1[0], x1[1]), cvtpk(x1[2], x1[3])}, p1 = {cvtpk(x2[0], x2[1]), cvtpk(x2[2], x2[3]), cvtpk(x3[0], x3[1]), cvtpk(x3[2], x3[3])};
;             a0 = __builtin_bit_cast(bf16x8, p0); a1 = __builtin_bit_cast(bf16x8, p1); }
;             const bf16x8 b00 = *(const bf16x8*)(b0p + k0), b01 = *(const bf16x8*)(b0p + k0 + 8), b10 = *(const bf16x8*)(b1p + k0), b11 = *(const bf16x8*)(b1p + k0 + 8);
;             acc0 = __builtin_amdgcn_mfma_f32_32x32x16_bf16(a0, b00, acc0, 0, 0, 0); acc0 = __builtin_amdgcn_mfma_f32_32x32x16_bf16(a1, b01, acc0, 0, 0, 0);
;             acc1 = __builtin_amdgcn_mfma_f32_32x32x16_bf16(a0, b10, acc1, 0, 0, 0); acc1 = __builtin_amdgcn_mfma_f32_32x32x16_bf16(a1, b11, acc1, 0, 0, 0); }
; #pragma unroll
;         for (int rg = 0; rg < 16; ++rg) { red[wave * 2048 + rg * 64 + lane] = acc0[rg]; red[wave * 2048 + (16 + rg) * 64 + lane] = acc1[rg]; }
;         __syncthreads();
; #pragma unroll
;         for (int q = 0; q < 4; ++q) { const int rr = 4 * wave + q; float v = 0.f;
; #pragma unroll
;             for (int w = 0; w < 8; ++w) v += red[w * 2048 + rr * 64 + lane];
;             E.el(row0 + crow(rr & 15, hh), col0 + (rr >> 4) * 32 + r32, v, r32); }
.LBB0_1418:
	s_ashr_i32 s6, s10, 31
	s_lshr_b32 s6, s6, 24
	s_add_i32 s6, s10, s6
	s_and_b32 s7, s6, 0xff00
	s_sub_i32 s7, s10, s7
	s_sext_i32_i16 s11, s7
	s_bfe_u32 s11, s11, 0x5001a
	s_add_i32 s11, s7, s11
	s_sext_i32_i16 s16, s11
	s_and_b32 s11, s11, 0xffe0
	s_sub_i32 s17, s7, s11
	s_lshl_b32 s7, s16, 1
	s_and_b32 s16, s7, 0xffffffc0
	s_lshl_b32 s6, s6, 2
	v_or_b32_e32 v2, s16, v34
	s_and_b32 s6, s6, 0xfffffc00
	v_ashrrev_i32_e32 v3, 31, v2
	s_sext_i32_i16 s26, s17
	s_add_i32 s6, s6, s8
	v_lshlrev_b64 v[2:3], 11, v[2:3]
	s_lshl_b32 s11, s26, 5
	v_lshl_add_u64 v[2:3], v[36:37], 0, v[2:3]
	s_ashr_i32 s7, s6, 31
	v_lshl_add_u64 v[66:67], s[6:7], 1, v[2:3]
	v_or_b32_e32 v2, s11, v34
	v_ashrrev_i32_e32 v3, 31, v2
	v_lshlrev_b64 v[2:3], 12, v[2:3]
	v_lshl_add_u64 v[2:3], v[38:39], 0, v[2:3]
	v_lshl_add_u64 v[68:69], s[6:7], 2, v[2:3]
	global_load_dwordx4 v[84:87], v[68:69], off offset:48
	global_load_dwordx4 v[88:91], v[68:69], off offset:32
	global_load_dwordx4 v[92:95], v[68:69], off offset:16
	global_load_dwordx4 v[96:99], v[68:69], off
	v_add_co_u32_e32 v70, vcc, s28, v66
	s_nop 1
	v_addc_co_u32_e32 v71, vcc, 0, v67, vcc
	global_load_dwordx4 v[100:103], v[66:67], off
	global_load_dwordx4 v[104:107], v[66:67], off offset:16
	global_load_dwordx4 v[108:111], v[70:71], off
	global_load_dwordx4 v[112:115], v[70:71], off offset:16
	global_load_dwordx4 v[116:119], v[68:69], off offset:176
	global_load_dwordx4 v[120:123], v[68:69], off offset:160
	global_load_dwordx4 v[124:127], v[68:69], off offset:144
	global_load_dwordx4 v[128:131], v[68:69], off offset:128
	global_load_dwordx4 v[132:135], v[66:67], off offset:64
	global_load_dwordx4 v[136:139], v[66:67], off offset:80
	global_load_dwordx4 v[140:143], v[70:71], off offset:64
	global_load_dwordx4 v[150:153], v[70:71], off offset:80
	s_add_i32 s16, s16, s9
	s_ashr_i32 s7, s26, 1
	s_ashr_i32 s6, s16, 7
	s_and_b32 s7, s7, -4
	s_add_i32 s6, s6, s7
	s_ashr_i32 s7, s6, 31
	s_lshl_b32 s17, s17, 2
	s_lshl_b64 s[6:7], s[6:7], 5
	s_and_b32 s17, s17, 28
	s_or_b32 s6, s6, s17
	v_and_b32_e32 v214, 16, v35
	s_add_i32 s10, s10, s27
	s_waitcnt vmcnt(15)
	v_cvt_pk_bf16_f32 v44, v84, v85
	v_cvt_pk_bf16_f32 v45, v86, v87
	s_waitcnt vmcnt(12)
	v_cvt_pk_bf16_f32 v18, v96, v97
	v_cvt_pk_bf16_f32 v19, v98, v99
	v_cvt_pk_bf16_f32 v20, v92, v93
	v_cvt_pk_bf16_f32 v21, v94, v95
	v_cvt_pk_bf16_f32 v42, v88, v89
	v_cvt_pk_bf16_f32 v43, v90, v91
	s_waitcnt vmcnt(11)
	v_mfma_f32_32x32x16_bf16 v[2:17], v[18:21], v[100:103], 0
	s_waitcnt vmcnt(10)
	v_mfma_f32_32x32x16_bf16 v[2:17], v[42:45], v[104:107], v[2:17]
	s_waitcnt vmcnt(9)
	v_mfma_f32_32x32x16_bf16 v[18:33], v[18:21], v[108:111], 0
	s_waitcnt vmcnt(8)
	v_mfma_f32_32x32x16_bf16 v[18:33], v[42:45], v[112:115], v[18:33]
	s_waitcnt vmcnt(6)
	v_cvt_pk_bf16_f32 v46, v120, v121
	v_cvt_pk_bf16_f32 v47, v122, v123
	s_waitcnt vmcnt(4)
	v_cvt_pk_bf16_f32 v54, v128, v129
	v_cvt_pk_bf16_f32 v55, v130, v131
	v_cvt_pk_bf16_f32 v56, v124, v125
	v_cvt_pk_bf16_f32 v57, v126, v127
	v_cvt_pk_bf16_f32 v48, v116, v117
	v_cvt_pk_bf16_f32 v49, v118, v119
	s_waitcnt vmcnt(3)
	v_mfma_f32_32x32x16_bf16 v[2:17], v[54:57], v[132:135], v[2:17]
	s_waitcnt vmcnt(1)
	v_mfma_f32_32x32x16_bf16 v[18:33], v[54:57], v[140:143], v[18:33]
	v_mfma_f32_32x32x16_bf16 v[2:17], v[46:49], v[136:139], v[2:17]
	s_waitcnt vmcnt(0)
	v_mfma_f32_32x32x16_bf16 v[18:33], v[46:49], v[150:153], v[18:33]
	global_load_dwordx4 v[84:87], v[68:69], off offset:304
	global_load_dwordx4 v[88:91], v[68:69], off offset:288
	global_load_dwordx4 v[92:95], v[68:69], off offset:272
	global_load_dwordx4 v[96:99], v[68:69], off offset:256
	global_load_dwordx4 v[100:103], v[66:67], off offset:128
	global_load_dwordx4 v[104:107], v[66:67], off offset:144
	global_load_dwordx4 v[108:111], v[70:71], off offset:128
	global_load_dwordx4 v[112:115], v[70:71], off offset:144
	global_load_dwordx4 v[116:119], v[68:69], off offset:432
	global_load_dwordx4 v[120:123], v[68:69], off offset:416
	global_load_dwordx4 v[124:127], v[68:69], off offset:400
	global_load_dwordx4 v[128:131], v[68:69], off offset:384
	global_load_dwordx4 v[132:135], v[66:67], off offset:192
	global_load_dwordx4 v[136:139], v[66:67], off offset:208
	global_load_dwordx4 v[140:143], v[70:71], off offset:192
	global_load_dwordx4 v[150:153], v[70:71], off offset:208
	s_waitcnt vmcnt(14)
	v_cvt_pk_bf16_f32 v46, v88, v89
	v_cvt_pk_bf16_f32 v47, v90, v91
	s_waitcnt vmcnt(12)
	v_cvt_pk_bf16_f32 v54, v96, v97
	v_cvt_pk_bf16_f32 v55, v98, v99
	v_cvt_pk_bf16_f32 v56, v92, v93
	v_cvt_pk_bf16_f32 v57, v94, v95
	v_cvt_pk_bf16_f32 v48, v84, v85
	v_cvt_pk_bf16_f32 v49, v86, v87
	s_waitcnt vmcnt(11)
	v_mfma_f32_32x32x16_bf16 v[2:17], v[54:57], v[100:103], v[2:17]
	s_waitcnt vmcnt(9)
	v_mfma_f32_32x32x16_bf16 v[18:33], v[54:57], v[108:111], v[18:33]
	v_mfma_f32_32x32x16_bf16 v[2:17], v[46:49], v[104:107], v[2:17]
	s_waitcnt vmcnt(8)
	v_mfma_f32_32x32x16_bf16 v[18:33], v[46:49], v[112:115], v[18:33]
	s_waitcnt vmcnt(6)
	v_cvt_pk_bf16_f32 v46, v120, v121
	v_cvt_pk_bf16_f32 v47, v122, v123
	s_waitcnt vmcnt(4)
	v_cvt_pk_bf16_f32 v54, v128, v129
	v_cvt_pk_bf16_f32 v55, v130, v131
	v_cvt_pk_bf16_f32 v56, v124, v125
	v_cvt_pk_bf16_f32 v57, v126, v127
	v_cvt_pk_bf16_f32 v48, v116, v117
	v_cvt_pk_bf16_f32 v49, v118, v119
	s_waitcnt vmcnt(3)
	v_mfma_f32_32x32x16_bf16 v[2:17], v[54:57], v[132:135], v[2:17]
	s_waitcnt vmcnt(1)
	v_mfma_f32_32x32x16_bf16 v[18:33], v[54:57], v[140:143], v[18:33]
	v_mfma_f32_32x32x16_bf16 v[2:17], v[46:49], v[136:139], v[2:17]
	s_waitcnt vmcnt(0)
	v_mfma_f32_32x32x16_bf16 v[18:33], v[46:49], v[150:153], v[18:33]
	s_nop 9
	ds_write2st64_b32 v40, v2, v3 offset1:1
	s_nop 0
	ds_write2st64_b32 v40, v18, v19 offset0:16 offset1:17
	ds_write2st64_b32 v40, v4, v5 offset0:2 offset1:3
	ds_write2st64_b32 v40, v20, v21 offset0:18 offset1:19
	ds_write2st64_b32 v40, v6, v7 offset0:4 offset1:5
	ds_write2st64_b32 v40, v22, v23 offset0:20 offset1:21
	ds_write2st64_b32 v40, v8, v9 offset0:6 offset1:7
	ds_write2st64_b32 v40, v24, v25 offset0:22 offset1:23
	ds_write2st64_b32 v40, v10, v11 offset0:8 offset1:9
	ds_write2st64_b32 v40, v26, v27 offset0:24 offset1:25
	ds_write2st64_b32 v40, v12, v13 offset0:10 offset1:11
	ds_write2st64_b32 v40, v28, v29 offset0:26 offset1:27
	ds_write2st64_b32 v40, v14, v15 offset0:12 offset1:13
	ds_write2st64_b32 v40, v30, v31 offset0:28 offset1:29
	ds_write2st64_b32 v40, v16, v17 offset0:14 offset1:15
	ds_write2st64_b32 v40, v32, v33 offset0:30 offset1:31
	s_waitcnt lgkmcnt(0)
	s_barrier
; __device__ __forceinline__ int crow(int r, int hi) { return (r & 3) + 8 * (r >> 2) + 4 * hi; }
; __device__ __forceinline__ int crow(int r, int hi) { return (r & 3) + 8 * (r >> 2) + 4 * hi; }
; __device__ __forceinline__ int crow(int r, int hi) { return (r & 3) + 8 * (r >> 2) + 4 * hi; }
; __device__ __forceinline__ int crow(int r, int hi) { return (r & 3) + 8 * (r >> 2) + 4 * hi; }
;     __device__ __forceinline__ void el(int row, int col, float v) const { if (col < nvalid) { if (act == 1) { v = v > 0.f ? v : 0.f; v = v * v; } C[(size_t)row * ldc + col] = v; } }
;     ...
; #pragma unroll
;         for (int q = 0; q < 4; ++q) { const int rr = 4 * wave + q; float v = 0.f;
; #pragma unroll
;             for (int w = 0; w < 8; ++w) v += red[w * 2048 + rr * 64 + lane];
;             E.el(row0 + crow(rr & 15, hh), col0 + (rr >> 4) * 32 + r32, v, r32); }
	ds_read2st64_b32 v[22:23], v41 offset1:1
	ds_read2st64_b32 v[20:21], v41 offset0:32 offset1:33
	ds_read2st64_b32 v[16:17], v41 offset0:64 offset1:65
	ds_read2st64_b32 v[14:15], v41 offset0:96 offset1:97
	ds_read2st64_b32 v[12:13], v41 offset0:128 offset1:129
	ds_read2st64_b32 v[10:11], v41 offset0:160 offset1:161
	ds_read2st64_b32 v[8:9], v41 offset0:192 offset1:193
	ds_read2st64_b32 v[6:7], v41 offset0:224 offset1:225
	s_waitcnt lgkmcnt(7)
	v_pk_add_f32 v[22:23], v[22:23], 0 op_sel_hi:[1,0]
	v_or_b32_e32 v2, s11, v35
	s_waitcnt lgkmcnt(6)
	v_pk_add_f32 v[20:21], v[22:23], v[20:21]
	v_or_b32_e32 v4, s16, v34
	s_waitcnt lgkmcnt(5)
	v_pk_add_f32 v[16:17], v[20:21], v[16:17]
	s_bfe_u32 s16, s16, 0x20005
	s_waitcnt lgkmcnt(4)
	v_pk_add_f32 v[14:15], v[16:17], v[14:15]
	v_ashrrev_i32_e32 v3, 31, v2
	s_waitcnt lgkmcnt(3)
	v_pk_add_f32 v[12:13], v[14:15], v[12:13]
	s_or_b32 s6, s6, s16
	s_waitcnt lgkmcnt(2)
	v_pk_add_f32 v[10:11], v[12:13], v[10:11]
	v_ashrrev_i32_e32 v5, 31, v4
	v_lshlrev_b64 v[18:19], 11, v[2:3]
	s_lshl_b64 s[6:7], s[6:7], 6
	v_lshlrev_b32_e32 v3, 3, v35
	v_or_b32_e32 v22, 1, v2
	s_waitcnt lgkmcnt(1)
	v_pk_add_f32 v[8:9], v[10:11], v[8:9]
	v_lshl_add_u64 v[4:5], v[4:5], 2, s[2:3]
	v_and_or_b32 v3, v3, 32, s6
	v_ashrrev_i32_e32 v23, 31, v22
	s_waitcnt lgkmcnt(0)
	v_pk_add_f32 v[6:7], v[8:9], v[6:7]
	v_lshl_add_u64 v[18:19], v[4:5], 0, v[18:19]
	v_or_b32_e32 v24, v3, v34
	v_lshlrev_b64 v[22:23], 11, v[22:23]
	v_and_b32_sdwa v3, v7, v239 dst_sel:DWORD dst_unused:UNUSED_PAD src0_sel:WORD_1 src1_sel:DWORD
	v_and_b32_sdwa v8, v6, v239 dst_sel:DWORD dst_unused:UNUSED_PAD src0_sel:WORD_1 src1_sel:DWORD
	v_lshl_add_u64 v[22:23], v[4:5], 0, v[22:23]
	global_store_dword v[18:19], v6, off
	global_store_dword v[22:23], v7, off
	v_add3_u32 v6, v6, v8, s66
	v_add3_u32 v3, v7, v3, s66
	s_mov_b32 s6, 0x7060302
	v_mov_b32_e32 v25, s7
	v_perm_b32 v3, v3, v6, s6
	ds_read2st64_b32 v[6:7], v41 offset0:2 offset1:3
	ds_read2st64_b32 v[8:9], v41 offset0:34 offset1:35
	ds_read2st64_b32 v[10:11], v41 offset0:66 offset1:67
	ds_read2st64_b32 v[12:13], v41 offset0:98 offset1:99
	v_lshlrev_b64 v[24:25], 5, v[24:25]
	v_lshl_add_u64 v[24:25], s[0:1], 0, v[24:25]
	v_lshl_add_u64 v[24:25], v[24:25], 0, v[214:215]
	v_bitop3_b32 v214, s11, 8, v35 bitop3:0xc8
	v_lshl_add_u64 v[26:27], v[24:25], 0, v[214:215]
	ds_read2st64_b32 v[14:15], v41 offset0:130 offset1:131
	ds_read2st64_b32 v[16:17], v41 offset0:162 offset1:163
	ds_read2st64_b32 v[18:19], v41 offset0:194 offset1:195
	ds_read2st64_b32 v[20:21], v41 offset0:226 offset1:227
	global_store_dword v[26:27], v3, off
	s_waitcnt lgkmcnt(7)
	v_add_f32_e32 v3, 0, v6
	s_waitcnt lgkmcnt(6)
	v_add_f32_e32 v3, v3, v8
	s_waitcnt lgkmcnt(5)
	v_add_f32_e32 v3, v3, v10
	s_waitcnt lgkmcnt(4)
	v_add_f32_e32 v3, v3, v12
	s_waitcnt lgkmcnt(3)
	v_add_f32_e32 v3, v3, v14
	s_waitcnt lgkmcnt(2)
	v_add_f32_e32 v3, v3, v16
	v_or_b32_e32 v22, 2, v2
	s_waitcnt lgkmcnt(1)
	v_add_f32_e32 v3, v3, v18
	v_ashrrev_i32_e32 v23, 31, v22
	s_waitcnt lgkmcnt(0)
	v_add_f32_e32 v3, v3, v20
	v_lshlrev_b64 v[22:23], 11, v[22:23]
	v_lshl_add_u64 v[22:23], v[4:5], 0, v[22:23]
	v_bfe_u32 v6, v3, 16, 1
	v_bitop3_b32 v214, v2, 8, 2 bitop3:0xc8
	global_store_dword v[22:23], v3, off
	v_add3_u32 v3, v3, v6, s66
	v_lshl_add_u64 v[22:23], v[24:25], 0, v[214:215]
	global_store_short_d16_hi v[22:23], v3, off offset:4
	v_add_f32_e32 v3, 0, v7
	v_add_f32_e32 v3, v3, v9
	v_add_f32_e32 v3, v3, v11
	v_add_f32_e32 v3, v3, v13
	v_add_f32_e32 v3, v3, v15
	v_or_b32_e32 v6, 3, v2
	v_add_f32_e32 v3, v3, v17
	v_ashrrev_i32_e32 v7, 31, v6
	v_add_f32_e32 v3, v3, v19
	v_lshlrev_b64 v[6:7], 11, v[6:7]
	v_add_f32_e32 v3, v3, v21
	v_lshl_add_u64 v[4:5], v[4:5], 0, v[6:7]
	global_store_dword v[4:5], v3, off
	v_bfe_u32 v4, v3, 16, 1
	v_bitop3_b32 v214, v2, 8, 3 bitop3:0xc8
	v_add3_u32 v4, v3, v4, s66
	v_lshl_add_u64 v[2:3], v[24:25], 0, v[214:215]
	s_cmpk_lt_i32 s10, 0x100
	global_store_short_d16_hi v[2:3], v4, off offset:6
	s_barrier
	s_cbranch_scc1 .LBB0_1418

; #define LAS __attribute__((address_space(3)))
; __device__ __forceinline__ int crow(int r, int hi) { return (r & 3) + 8 * (r >> 2) + 4 * hi; }
; __device__ __forceinline__ int crow(int r, int hi) { return (r & 3) + 8 * (r >> 2) + 4 * hi; }
; __device__ __forceinline__ int crow(int r, int hi) { return (r & 3) + 8 * (r >> 2) + 4 * hi; }
; __device__ __forceinline__ int crow(int r, int hi) { return (r & 3) + 8 * (r >> 2) + 4 * hi; }
;     __device__ __forceinline__ void el(int row, int col, float v) const { if (col < nvalid) { if (act == 1) { v = v > 0.f ? v : 0.f; v = v * v; } C[(size_t)row * ldc + col] = v; } }
; template <class Epi>
; __device__ __forceinline__ void wgemm_wg_ln(const LnSrc& L, const bf16* Bt, int M, int N, const Epi& E, int G, int tid, LAS unsigned char* lds) {
;     ...
;     for (int nbk = cg; nbk < NBK; nbk += ncg) { const int col0 = 64 * nbk;
;         __syncthreads();
;         f32x16 acc0 = {}, acc1 = {}; const int kbeg = wave * KW;
;         const bf16* b0p = Bt + (size_t)(col0 + r32) * K + 16 * hh + kbeg; const bf16* b1p = b0p + (size_t)32 * K; LAS unsigned char* prow = panel + r32 * 2048;
; #pragma unroll
;         for (int k0 = 0; k0 < KW; k0 += 32) { const int ch = (kbeg + k0 + 16 * hh) >> 3;
;             const bf16x8 a0 = *(const LAS bf16x8*)(prow + ((ch ^ (r32 & 15)) << 4)), a1 = *(const LAS bf16x8*)(prow + (((ch + 1) ^ (r32 & 15)) << 4));
;             const bf16x8 b00 = *(const bf16x8*)(b0p + k0), b01 = *(const bf16x8*)(b0p + k0 + 8), b10 = *(const bf16x8*)(b1p + k0), b11 = *(const bf16x8*)(b1p + k0 + 8);
;             acc0 = __builtin_amdgcn_mfma_f32_32x32x16_bf16(a0, b00, acc0, 0, 0, 0); acc0 = __builtin_amdgcn_mfma_f32_32x32x16_bf16(a1, b01, acc0, 0, 0, 0);
;             acc1 = __builtin_amdgcn_mfma_f32_32x32x16_bf16(a0, b10, acc1, 0, 0, 0); acc1 = __builtin_amdgcn_mfma_f32_32x32x16_bf16(a1, b11, acc1, 0, 0, 0); }
; #pragma unroll
;         for (int rg = 0; rg < 16; ++rg) { red[wave * 2048 + rg * 64 + lane] = acc0[rg]; red[wave * 2048 + (16 + rg) * 64 + lane] = acc1[rg]; }
;         __syncthreads();
; #pragma unroll
;         for (int q = 0; q < 4; ++q) { const int rr = 4 * wave + q; float v = 0.f;
; #pragma unroll
;             for (int w = 0; w < 8; ++w) v += red[w * 2048 + rr * 64 + lane];
;             E.el(row0 + crow(rr & 15, hh), col0 + (rr >> 4) * 32 + r32, v, r32); }
.LBB0_1454:
	v_ashrrev_i32_e32 v45, 31, v44
	v_lshlrev_b64 v[2:3], 11, v[44:45]
	v_lshl_add_u64 v[46:47], v[34:35], 0, v[2:3]
	s_waitcnt lgkmcnt(0)
	s_barrier
	global_load_dwordx4 v[84:87], v[46:47], off
	global_load_dwordx4 v[88:91], v[46:47], off offset:16
	v_add_co_u32_e32 v74, vcc, 0x10000, v46
	s_nop 1
	v_addc_co_u32_e32 v75, vcc, 0, v47, vcc
	global_load_dwordx4 v[92:95], v[74:75], off
	global_load_dwordx4 v[96:99], v[74:75], off offset:16
	s_movk_i32 s0, 0x200
	global_load_dwordx4 v[100:103], v[46:47], off offset:64
	global_load_dwordx4 v[104:107], v[74:75], off offset:64
	global_load_dwordx4 v[108:111], v[46:47], off offset:80
	global_load_dwordx4 v[112:115], v[74:75], off offset:80
	global_load_dwordx4 v[116:119], v[46:47], off offset:128
	global_load_dwordx4 v[120:123], v[74:75], off offset:128
	global_load_dwordx4 v[124:127], v[46:47], off offset:144
	global_load_dwordx4 v[128:131], v[74:75], off offset:144
	global_load_dwordx4 v[132:135], v[46:47], off offset:192
	global_load_dwordx4 v[136:139], v[74:75], off offset:192
	global_load_dwordx4 v[140:143], v[46:47], off offset:208
	v_add_u32_e32 v46, s3, v44
	global_load_dwordx4 v[150:153], v[74:75], off offset:208
	ds_read_b128 v[6:9], v49
	ds_read_b128 v[62:65], v50
	ds_read_b128 v[70:73], v51
	s_waitcnt lgkmcnt(2)
	s_waitcnt vmcnt(15)
	v_mfma_f32_32x32x16_bf16 v[18:33], v[6:9], v[84:87], 0
	s_waitcnt lgkmcnt(1)
	s_waitcnt vmcnt(14)
	v_mfma_f32_32x32x16_bf16 v[18:33], v[62:65], v[88:91], v[18:33]
	s_waitcnt vmcnt(13)
	v_mfma_f32_32x32x16_bf16 v[2:17], v[6:9], v[92:95], 0
	s_waitcnt vmcnt(12)
	v_mfma_f32_32x32x16_bf16 v[2:17], v[62:65], v[96:99], v[2:17]
	ds_read_b128 v[66:69], v52
	s_waitcnt lgkmcnt(1)
	s_waitcnt vmcnt(11)
	v_mfma_f32_32x32x16_bf16 v[18:33], v[70:73], v[100:103], v[18:33]
	s_waitcnt vmcnt(10)
	v_mfma_f32_32x32x16_bf16 v[2:17], v[70:73], v[104:107], v[2:17]
	ds_read_b128 v[70:73], v53
	s_waitcnt lgkmcnt(1)
	s_waitcnt vmcnt(9)
	v_mfma_f32_32x32x16_bf16 v[18:33], v[66:69], v[108:111], v[18:33]
	s_waitcnt vmcnt(8)
	v_mfma_f32_32x32x16_bf16 v[2:17], v[66:69], v[112:115], v[2:17]
	ds_read_b128 v[66:69], v54
	s_waitcnt lgkmcnt(1)
	s_waitcnt vmcnt(7)
	v_mfma_f32_32x32x16_bf16 v[18:33], v[70:73], v[116:119], v[18:33]
	s_waitcnt vmcnt(6)
	v_mfma_f32_32x32x16_bf16 v[2:17], v[70:73], v[120:123], v[2:17]
	ds_read_b128 v[70:73], v55
	s_waitcnt lgkmcnt(1)
	s_waitcnt vmcnt(5)
	v_mfma_f32_32x32x16_bf16 v[18:33], v[66:69], v[124:127], v[18:33]
	s_waitcnt vmcnt(4)
	v_mfma_f32_32x32x16_bf16 v[2:17], v[66:69], v[128:131], v[2:17]
	s_waitcnt lgkmcnt(0)
	s_waitcnt vmcnt(3)
	v_mfma_f32_32x32x16_bf16 v[18:33], v[70:73], v[132:135], v[18:33]
	v_cmp_gt_i32_e32 vcc, s0, v46
	s_waitcnt vmcnt(2)
	v_mfma_f32_32x32x16_bf16 v[2:17], v[70:73], v[136:139], v[2:17]
	ds_read_b128 v[62:65], v56
	s_waitcnt lgkmcnt(0)
	s_waitcnt vmcnt(1)
	v_mfma_f32_32x32x16_bf16 v[18:33], v[62:65], v[140:143], v[18:33]
	s_waitcnt vmcnt(0)
	v_mfma_f32_32x32x16_bf16 v[2:17], v[62:65], v[150:153], v[2:17]
	s_nop 8
	ds_write2st64_b32 v48, v18, v19 offset1:1
	ds_write2st64_b32 v48, v20, v21 offset0:2 offset1:3
	ds_write2st64_b32 v48, v22, v23 offset0:4 offset1:5
	ds_write2st64_b32 v48, v24, v25 offset0:6 offset1:7
	ds_write2st64_b32 v48, v26, v27 offset0:8 offset1:9
	ds_write2st64_b32 v48, v28, v29 offset0:10 offset1:11
	ds_write2st64_b32 v48, v30, v31 offset0:12 offset1:13
	ds_write2st64_b32 v48, v32, v33 offset0:14 offset1:15
	ds_write2st64_b32 v48, v2, v3 offset0:16 offset1:17
	ds_write2st64_b32 v48, v4, v5 offset0:18 offset1:19
	ds_write2st64_b32 v48, v6, v7 offset0:20 offset1:21
	ds_write2st64_b32 v48, v8, v9 offset0:22 offset1:23
	ds_write2st64_b32 v48, v10, v11 offset0:24 offset1:25
	ds_write2st64_b32 v48, v12, v13 offset0:26 offset1:27
	ds_write2st64_b32 v48, v14, v15 offset0:28 offset1:29
	ds_write2st64_b32 v48, v16, v17 offset0:30 offset1:31
	s_waitcnt lgkmcnt(0)
	s_barrier
	s_and_saveexec_b64 s[0:1], vcc
	s_cbranch_execz .LBB0_1453
	ds_read2st64_b32 v[4:5], v57 offset1:1
	ds_read2st64_b32 v[6:7], v57 offset0:32 offset1:33
	ds_read2st64_b32 v[8:9], v57 offset0:64 offset1:65
	ds_read2st64_b32 v[10:11], v57 offset0:96 offset1:97
	ds_read2st64_b32 v[12:13], v57 offset0:128 offset1:129
	ds_read2st64_b32 v[14:15], v57 offset0:160 offset1:161
	ds_read2st64_b32 v[16:17], v57 offset0:192 offset1:193
	ds_read2st64_b32 v[18:19], v57 offset0:224 offset1:225
	s_waitcnt lgkmcnt(7)
	v_add_f32_e32 v2, 0, v4
	s_waitcnt lgkmcnt(6)
	v_add_f32_e32 v2, v2, v6
	s_waitcnt lgkmcnt(5)
	v_add_f32_e32 v2, v2, v8
	s_waitcnt lgkmcnt(4)
	v_add_f32_e32 v2, v2, v10
	s_waitcnt lgkmcnt(3)
	v_add_f32_e32 v2, v2, v12
	s_waitcnt lgkmcnt(2)
	v_add_f32_e32 v2, v2, v14
	s_waitcnt lgkmcnt(1)
	v_add_f32_e32 v2, v2, v16
	v_ashrrev_i32_e32 v47, 31, v46
	s_waitcnt lgkmcnt(0)
	v_add_f32_e32 v4, v2, v18
	v_lshlrev_b64 v[2:3], 2, v[46:47]
	v_lshl_add_u64 v[20:21], v[36:37], 0, v[2:3]
	global_store_dword v[20:21], v4, off
	v_add_f32_e32 v4, 0, v5
	v_add_f32_e32 v4, v4, v7
	v_add_f32_e32 v4, v4, v9
	v_add_f32_e32 v4, v4, v11
	v_add_f32_e32 v4, v4, v13
	v_add_f32_e32 v4, v4, v15
	v_add_f32_e32 v4, v4, v17
	v_add_f32_e32 v6, v4, v19
	v_lshl_add_u64 v[4:5], v[38:39], 0, v[2:3]
	global_store_dword v[4:5], v6, off
	ds_read2st64_b32 v[4:5], v57 offset0:2 offset1:3
	ds_read2st64_b32 v[6:7], v57 offset0:34 offset1:35
	ds_read2st64_b32 v[8:9], v57 offset0:66 offset1:67
	ds_read2st64_b32 v[10:11], v57 offset0:98 offset1:99
	ds_read2st64_b32 v[12:13], v57 offset0:130 offset1:131
	ds_read2st64_b32 v[14:15], v57 offset0:162 offset1:163
	ds_read2st64_b32 v[16:17], v57 offset0:194 offset1:195
	ds_read2st64_b32 v[18:19], v57 offset0:226 offset1:227
	s_waitcnt lgkmcnt(7)
	v_add_f32_e32 v4, 0, v4
	s_waitcnt lgkmcnt(6)
	v_add_f32_e32 v4, v4, v6
	s_waitcnt lgkmcnt(5)
	v_add_f32_e32 v4, v4, v8
	s_waitcnt lgkmcnt(4)
	v_add_f32_e32 v4, v4, v10
	s_waitcnt lgkmcnt(3)
	v_add_f32_e32 v4, v4, v12
	s_waitcnt lgkmcnt(2)
	v_add_f32_e32 v4, v4, v14
	s_waitcnt lgkmcnt(1)
	v_add_f32_e32 v4, v4, v16
	s_waitcnt lgkmcnt(0)
	v_add_f32_e32 v4, v4, v18
	v_lshl_add_u64 v[20:21], v[40:41], 0, v[2:3]
	global_store_dword v[20:21], v4, off
	v_add_f32_e32 v4, 0, v5
	v_add_f32_e32 v4, v4, v7
	v_add_f32_e32 v4, v4, v9
	v_add_f32_e32 v4, v4, v11
	v_add_f32_e32 v4, v4, v13
	v_add_f32_e32 v4, v4, v15
	v_add_f32_e32 v4, v4, v17
	v_add_f32_e32 v4, v4, v19
	v_lshl_add_u64 v[2:3], v[42:43], 0, v[2:3]
	global_store_dword v[2:3], v4, off
	s_branch .LBB0_1453

;     ...
;     for (int it = (int)blockIdx.x - wg_lo; it < NIT; it += wg_n) { const int ks = it / nT, it2 = it % nT, mb = it2 % nMb, nbk = it2 / nMb, row0 = 32 * mb, col0 = 64 * nbk, kbeg = (ks * 8 + wave) * KW;
;         f32x16 acc0 = {}, acc1 = {};
;         const bf16* b0p = Bt + (size_t)(col0 + r32) * K + 16 * hh + kbeg; const bf16* b1p = b0p + (size_t)32 * K; const float* af = (const float*)Av + (size_t)(row0 + r32) * lda + 16 * hh + kbeg; const bf16* ab = (const bf16*)Av + (size_t)(row0 + r32) * lda + 16 * hh + kbeg;
; #pragma unroll
;         for (int k0 = 0; k0 < KW; k0 += 32) { bf16x8 a0, a1;
;           if (ABF) { a0 = *(const bf16x8*)(ab + k0); a1 = *(const bf16x8*)(ab + k0 + 8); } else {
;             const f32x4 x0 = *(const f32x4*)(af + k0), x1 = *(const f32x4*)(af + k0 + 4), x2 = *(const f32x4*)(af + k0 + 8), x3 = *(const f32x4*)(af + k0 + 12);
;             const u32x4_t p0 = {cvtpk(x0[0], x0[1]), cvtpk(x0[2], x0[3]), cvtpk(x1[0], x1[1]), cvtpk(x1[2], x1[3])}, p1 = {cvtpk(x2[0], x2[1]), cvtpk(x2[2], x2[3]), cvtpk(x3[0], x3[1]), cvtpk(x3[2], x3[3])};
;             a0 = __builtin_bit_cast(bf16x8, p0); a1 = __builtin_bit_cast(bf16x8, p1); }
;             const bf16x8 b00 = *(const bf16x8*)(b0p + k0), b01 = *(const bf16x8*)(b0p + k0 + 8), b10 = *(const bf16x8*)(b1p + k0), b11 = *(const bf16x8*)(b1p + k0 + 8);
;             acc0 = __builtin_amdgcn_mfma_f32_32x32x16_bf16(a0, b00, acc0, 0, 0, 0); acc0 = __builtin_amdgcn_mfma_f32_32x32x16_bf16(a1, b01, acc0, 0, 0, 0);
;             acc1 = __builtin_amdgcn_mfma_f32_32x32x16_bf16(a0, b10, acc1, 0, 0, 0); acc1 = __builtin_amdgcn_mfma_f32_32x32x16_bf16(a1, b11, acc1, 0, 0, 0); }
; #pragma unroll
;         for (int rg = 0; rg < 16; ++rg) { red[wave * 2048 + rg * 64 + lane] = acc0[rg]; red[wave * 2048 + (16 + rg) * 64 + lane] = acc1[rg]; }
.LBB0_1649:
	s_ashr_i32 s2, s7, 31
	s_lshr_b32 s2, s2, 25
	s_add_i32 s3, s7, s2
	s_and_b32 s2, s3, 0xff80
	s_sub_i32 s2, s7, s2
	s_bfe_i32 s8, s2, 0x80000
	s_bfe_u32 s8, s8, 0x3000c
	s_add_i32 s8, s2, s8
	s_bfe_i32 s9, s8, 0x80000
	s_and_b32 s8, s8, 0xf8
	s_sub_i32 s2, s2, s8
	s_sext_i32_i16 s9, s9
	s_sext_i32_i8 s2, s2
	s_lshl_b32 s8, s2, 5
	s_lshl_b32 s2, s9, 3
	s_andn2_b32 s2, s2, 63
	s_lshl_b32 s3, s3, 2
	v_or_b32_e32 v2, s2, v38
	s_and_b32 s3, s3, 0xfffffe00
	v_ashrrev_i32_e32 v3, 31, v2
	s_add_i32 s10, s3, s6
	v_lshlrev_b64 v[2:3], 10, v[2:3]
	v_lshl_add_u64 v[2:3], v[34:35], 0, v[2:3]
	s_ashr_i32 s11, s10, 31
	v_lshl_add_u64 v[60:61], s[10:11], 1, v[2:3]
	v_or_b32_e32 v2, s8, v38
	v_ashrrev_i32_e32 v3, 31, v2
	v_lshlrev_b64 v[2:3], 11, v[2:3]
	v_lshl_add_u64 v[2:3], v[36:37], 0, v[2:3]
	v_lshl_add_u64 v[56:57], s[10:11], 2, v[2:3]
	global_load_dwordx4 v[84:87], v[56:57], off offset:48
	global_load_dwordx4 v[88:91], v[56:57], off offset:32
	global_load_dwordx4 v[92:95], v[56:57], off offset:16
	global_load_dwordx4 v[96:99], v[56:57], off
	v_add_co_u32_e32 v64, vcc, s33, v60
	s_nop 1
	global_load_dwordx4 v[100:103], v[60:61], off
	global_load_dwordx4 v[104:107], v[60:61], off offset:16
	v_addc_co_u32_e32 v65, vcc, 0, v61, vcc
	global_load_dwordx4 v[108:111], v[64:65], off
	global_load_dwordx4 v[112:115], v[64:65], off offset:16
	global_load_dwordx4 v[116:119], v[56:57], off offset:176
	global_load_dwordx4 v[120:123], v[56:57], off offset:160
	global_load_dwordx4 v[124:127], v[56:57], off offset:144
	global_load_dwordx4 v[128:131], v[56:57], off offset:128
	global_load_dwordx4 v[132:135], v[60:61], off offset:64
	global_load_dwordx4 v[136:139], v[60:61], off offset:80
	global_load_dwordx4 v[140:143], v[64:65], off offset:64
	global_load_dwordx4 v[150:153], v[64:65], off offset:80
	s_waitcnt vmcnt(15)
	v_cvt_pk_bf16_f32 v46, v84, v85
	v_cvt_pk_bf16_f32 v47, v86, v87
	s_waitcnt vmcnt(12)
	v_cvt_pk_bf16_f32 v18, v96, v97
	v_cvt_pk_bf16_f32 v19, v98, v99
	v_cvt_pk_bf16_f32 v20, v92, v93
	v_cvt_pk_bf16_f32 v21, v94, v95
	v_cvt_pk_bf16_f32 v44, v88, v89
	v_cvt_pk_bf16_f32 v45, v90, v91
	s_waitcnt vmcnt(11)
	v_mfma_f32_32x32x16_bf16 v[2:17], v[18:21], v[100:103], 0
	s_waitcnt vmcnt(10)
	v_mfma_f32_32x32x16_bf16 v[2:17], v[44:47], v[104:107], v[2:17]
	s_waitcnt vmcnt(9)
	v_mfma_f32_32x32x16_bf16 v[18:33], v[18:21], v[108:111], 0
	s_waitcnt vmcnt(8)
	v_mfma_f32_32x32x16_bf16 v[18:33], v[44:47], v[112:115], v[18:33]
	s_waitcnt vmcnt(6)
	v_cvt_pk_bf16_f32 v48, v120, v121
	v_cvt_pk_bf16_f32 v49, v122, v123
	s_waitcnt vmcnt(4)
	v_cvt_pk_bf16_f32 v56, v128, v129
	v_cvt_pk_bf16_f32 v57, v130, v131
	v_cvt_pk_bf16_f32 v58, v124, v125
	v_cvt_pk_bf16_f32 v59, v126, v127
	v_cvt_pk_bf16_f32 v50, v116, v117
	v_cvt_pk_bf16_f32 v51, v118, v119
	s_waitcnt vmcnt(3)
	v_mfma_f32_32x32x16_bf16 v[2:17], v[56:59], v[132:135], v[2:17]
	s_waitcnt vmcnt(1)
	v_mfma_f32_32x32x16_bf16 v[18:33], v[56:59], v[140:143], v[18:33]
	v_mfma_f32_32x32x16_bf16 v[2:17], v[48:51], v[136:139], v[2:17]
	s_waitcnt vmcnt(0)
	v_mfma_f32_32x32x16_bf16 v[18:33], v[48:51], v[150:153], v[18:33]
	s_nop 9
	ds_write2st64_b32 v40, v2, v3 offset1:1
	s_nop 0
	ds_write2st64_b32 v40, v18, v19 offset0:16 offset1:17
	ds_write2st64_b32 v40, v4, v5 offset0:2 offset1:3
	ds_write2st64_b32 v40, v20, v21 offset0:18 offset1:19
	ds_write2st64_b32 v40, v6, v7 offset0:4 offset1:5
	ds_write2st64_b32 v40, v22, v23 offset0:20 offset1:21
	ds_write2st64_b32 v40, v8, v9 offset0:6 offset1:7
	ds_write2st64_b32 v40, v24, v25 offset0:22 offset1:23
	ds_write2st64_b32 v40, v10, v11 offset0:8 offset1:9
	ds_write2st64_b32 v40, v26, v27 offset0:24 offset1:25
	ds_write2st64_b32 v40, v12, v13 offset0:10 offset1:11
	ds_write2st64_b32 v40, v28, v29 offset0:26 offset1:27
	ds_write2st64_b32 v40, v14, v15 offset0:12 offset1:13
	ds_write2st64_b32 v40, v30, v31 offset0:28 offset1:29
	ds_write2st64_b32 v40, v16, v17 offset0:14 offset1:15
	ds_write2st64_b32 v40, v32, v33 offset0:30 offset1:31
	v_add_u32_e32 v4, s2, v41
	s_movk_i32 s2, 0x400
	v_cmp_gt_i32_e32 vcc, s2, v4
	s_waitcnt lgkmcnt(0)
	s_barrier
; __device__ __forceinline__ int crow(int r, int hi) { return (r & 3) + 8 * (r >> 2) + 4 * hi; }
; __device__ __forceinline__ int crow(int r, int hi) { return (r & 3) + 8 * (r >> 2) + 4 * hi; }
; __device__ __forceinline__ int crow(int r, int hi) { return (r & 3) + 8 * (r >> 2) + 4 * hi; }
; __device__ __forceinline__ int crow(int r, int hi) { return (r & 3) + 8 * (r >> 2) + 4 * hi; }
;     __device__ __forceinline__ void el(int row, int col, float v) const { if (col < nvalid) { if (act == 1) { v = v > 0.f ? v : 0.f; v = v * v; } C[(size_t)row * ldc + col] = v; } }
;     ...
; #pragma unroll
;         for (int q = 0; q < 4; ++q) { const int rr = 4 * wave + q; float v = 0.f;
; #pragma unroll
;             for (int w = 0; w < 8; ++w) v += red[w * 2048 + rr * 64 + lane];
;             E.el(row0 + crow(rr & 15, hh), col0 + (rr >> 4) * 32 + r32, v, r32); }
	s_and_saveexec_b64 s[2:3], vcc
	s_cbranch_execz .LBB0_1648
	ds_read2st64_b32 v[6:7], v42 offset1:1
	ds_read2st64_b32 v[8:9], v42 offset0:32 offset1:33
	ds_read2st64_b32 v[10:11], v42 offset0:64 offset1:65
	ds_read2st64_b32 v[12:13], v42 offset0:96 offset1:97
	ds_read2st64_b32 v[14:15], v42 offset0:128 offset1:129
	ds_read2st64_b32 v[16:17], v42 offset0:160 offset1:161
	ds_read2st64_b32 v[18:19], v42 offset0:192 offset1:193
	ds_read2st64_b32 v[20:21], v42 offset0:224 offset1:225
	s_waitcnt lgkmcnt(7)
	v_add_f32_e32 v3, 0, v6
	s_waitcnt lgkmcnt(6)
	v_add_f32_e32 v3, v3, v8
	s_waitcnt lgkmcnt(5)
	v_add_f32_e32 v3, v3, v10
	s_waitcnt lgkmcnt(4)
	v_add_f32_e32 v3, v3, v12
	s_waitcnt lgkmcnt(3)
	v_add_f32_e32 v3, v3, v14
	s_waitcnt lgkmcnt(2)
	v_add_f32_e32 v3, v3, v16
	v_or_b32_e32 v2, s8, v39
	s_waitcnt lgkmcnt(1)
	v_add_f32_e32 v3, v3, v18
	s_waitcnt lgkmcnt(0)
	v_add_f32_e32 v6, v3, v20
	v_ashrrev_i32_e32 v3, 31, v2
	v_ashrrev_i32_e32 v5, 31, v4
	v_lshlrev_b64 v[22:23], 12, v[2:3]
	v_add_f32_e32 v3, 0, v7
	v_lshl_add_u64 v[22:23], s[0:1], 0, v[22:23]
	v_lshlrev_b64 v[4:5], 2, v[4:5]
	v_add_f32_e32 v3, v3, v9
	v_lshl_add_u64 v[22:23], v[22:23], 0, v[4:5]
	v_add_f32_e32 v3, v3, v11
	global_store_dword v[22:23], v6, off
	v_or_b32_e32 v6, 1, v2
	v_add_f32_e32 v3, v3, v13
	v_add_f32_e32 v3, v3, v15
	v_ashrrev_i32_e32 v7, 31, v6
	v_add_f32_e32 v3, v3, v17
	v_lshlrev_b64 v[6:7], 12, v[6:7]
	v_add_f32_e32 v3, v3, v19
	v_lshl_add_u64 v[6:7], s[0:1], 0, v[6:7]
	v_add_f32_e32 v3, v3, v21
	v_lshl_add_u64 v[6:7], v[6:7], 0, v[4:5]
	global_store_dword v[6:7], v3, off
	ds_read2st64_b32 v[6:7], v42 offset0:2 offset1:3
	ds_read2st64_b32 v[10:11], v42 offset0:34 offset1:35
	ds_read2st64_b32 v[12:13], v42 offset0:66 offset1:67
	ds_read2st64_b32 v[14:15], v42 offset0:98 offset1:99
	ds_read2st64_b32 v[16:17], v42 offset0:130 offset1:131
	ds_read2st64_b32 v[18:19], v42 offset0:162 offset1:163
	ds_read2st64_b32 v[20:21], v42 offset0:194 offset1:195
	ds_read2st64_b32 v[22:23], v42 offset0:226 offset1:227
	s_waitcnt lgkmcnt(7)
	v_add_f32_e32 v3, 0, v6
	s_waitcnt lgkmcnt(6)
	v_add_f32_e32 v3, v3, v10
	s_waitcnt lgkmcnt(5)
	v_add_f32_e32 v3, v3, v12
	v_or_b32_e32 v8, 2, v2
	s_waitcnt lgkmcnt(4)
	v_add_f32_e32 v3, v3, v14
	s_waitcnt lgkmcnt(3)
	v_add_f32_e32 v3, v3, v16
	v_ashrrev_i32_e32 v9, 31, v8
	s_waitcnt lgkmcnt(2)
	v_add_f32_e32 v3, v3, v18
	v_lshlrev_b64 v[8:9], 12, v[8:9]
	s_waitcnt lgkmcnt(1)
	v_add_f32_e32 v3, v3, v20
	v_lshl_add_u64 v[8:9], s[0:1], 0, v[8:9]
	s_waitcnt lgkmcnt(0)
	v_add_f32_e32 v3, v3, v22
	v_lshl_add_u64 v[8:9], v[8:9], 0, v[4:5]
	global_store_dword v[8:9], v3, off
	v_add_f32_e32 v3, 0, v7
	v_add_f32_e32 v3, v3, v11
	v_add_f32_e32 v3, v3, v13
	v_add_f32_e32 v3, v3, v15
	v_add_f32_e32 v3, v3, v17
	v_add_f32_e32 v3, v3, v19
	v_or_b32_e32 v2, 3, v2
	v_add_f32_e32 v3, v3, v21
	v_add_f32_e32 v6, v3, v23
	v_ashrrev_i32_e32 v3, 31, v2
	v_lshlrev_b64 v[2:3], 12, v[2:3]
	v_lshl_add_u64 v[2:3], s[0:1], 0, v[2:3]
	v_lshl_add_u64 v[2:3], v[2:3], 0, v[4:5]
	global_store_dword v[2:3], v6, off
	s_branch .LBB0_1648

; #define LAS __attribute__((address_space(3)))
; __device__ __forceinline__ int crow(int r, int hi) { return (r & 3) + 8 * (r >> 2) + 4 * hi; }
; __device__ __forceinline__ int crow(int r, int hi) { return (r & 3) + 8 * (r >> 2) + 4 * hi; }
; __device__ __forceinline__ int crow(int r, int hi) { return (r & 3) + 8 * (r >> 2) + 4 * hi; }
; __device__ __forceinline__ int crow(int r, int hi) { return (r & 3) + 8 * (r >> 2) + 4 * hi; }
;     __device__ __forceinline__ void el(int row, int col, float v) const { if (col < nvalid) { if (act == 1) { v = v > 0.f ? v : 0.f; v = v * v; } C[(size_t)row * ldc + col] = v; } }
; template <class Epi>
; __device__ __forceinline__ void wgemm_wg_ln(const LnSrc& L, const bf16* Bt, int M, int N, const Epi& E, int G, int tid, LAS unsigned char* lds) {
;     ...
;     for (int nbk = cg; nbk < NBK; nbk += ncg) { const int col0 = 64 * nbk;
;         __syncthreads();
;         f32x16 acc0 = {}, acc1 = {}; const int kbeg = wave * KW;
;         const bf16* b0p = Bt + (size_t)(col0 + r32) * K + 16 * hh + kbeg; const bf16* b1p = b0p + (size_t)32 * K; LAS unsigned char* prow = panel + r32 * 2048;
; #pragma unroll
;         for (int k0 = 0; k0 < KW; k0 += 32) { const int ch = (kbeg + k0 + 16 * hh) >> 3;
;             const bf16x8 a0 = *(const LAS bf16x8*)(prow + ((ch ^ (r32 & 15)) << 4)), a1 = *(const LAS bf16x8*)(prow + (((ch + 1) ^ (r32 & 15)) << 4));
;             const bf16x8 b00 = *(const bf16x8*)(b0p + k0), b01 = *(const bf16x8*)(b0p + k0 + 8), b10 = *(const bf16x8*)(b1p + k0), b11 = *(const bf16x8*)(b1p + k0 + 8);
;             acc0 = __builtin_amdgcn_mfma_f32_32x32x16_bf16(a0, b00, acc0, 0, 0, 0); acc0 = __builtin_amdgcn_mfma_f32_32x32x16_bf16(a1, b01, acc0, 0, 0, 0);
;             acc1 = __builtin_amdgcn_mfma_f32_32x32x16_bf16(a0, b10, acc1, 0, 0, 0); acc1 = __builtin_amdgcn_mfma_f32_32x32x16_bf16(a1, b11, acc1, 0, 0, 0); }
; #pragma unroll
;         for (int rg = 0; rg < 16; ++rg) { red[wave * 2048 + rg * 64 + lane] = acc0[rg]; red[wave * 2048 + (16 + rg) * 64 + lane] = acc1[rg]; }
;         __syncthreads();
; #pragma unroll
;         for (int q = 0; q < 4; ++q) { const int rr = 4 * wave + q; float v = 0.f;
; #pragma unroll
;             for (int w = 0; w < 8; ++w) v += red[w * 2048 + rr * 64 + lane];
;             E.el(row0 + crow(rr & 15, hh), col0 + (rr >> 4) * 32 + r32, v, r32); }
.LBB0_1758:
	v_ashrrev_i32_e32 v45, 31, v44
	v_lshlrev_b64 v[2:3], 11, v[44:45]
	v_lshl_add_u64 v[46:47], v[34:35], 0, v[2:3]
	s_waitcnt lgkmcnt(0)
	s_barrier
	global_load_dwordx4 v[84:87], v[46:47], off
	global_load_dwordx4 v[88:91], v[46:47], off offset:16
	v_add_co_u32_e32 v74, vcc, 0x10000, v46
	s_nop 1
	v_addc_co_u32_e32 v75, vcc, 0, v47, vcc
	global_load_dwordx4 v[92:95], v[74:75], off
	global_load_dwordx4 v[96:99], v[74:75], off offset:16
	global_load_dwordx4 v[100:103], v[46:47], off offset:64
	global_load_dwordx4 v[104:107], v[74:75], off offset:64
	global_load_dwordx4 v[108:111], v[46:47], off offset:80
	global_load_dwordx4 v[112:115], v[74:75], off offset:80
	global_load_dwordx4 v[116:119], v[46:47], off offset:128
	global_load_dwordx4 v[120:123], v[74:75], off offset:128
	global_load_dwordx4 v[124:127], v[46:47], off offset:144
	global_load_dwordx4 v[128:131], v[74:75], off offset:144
	global_load_dwordx4 v[132:135], v[46:47], off offset:192
	global_load_dwordx4 v[136:139], v[74:75], off offset:192
	global_load_dwordx4 v[140:143], v[46:47], off offset:208
	v_add_u32_e32 v46, s2, v44
	global_load_dwordx4 v[150:153], v[74:75], off offset:208
	ds_read_b128 v[6:9], v49
	ds_read_b128 v[62:65], v50
	ds_read_b128 v[70:73], v51
	s_waitcnt lgkmcnt(2)
	s_waitcnt vmcnt(15)
	v_mfma_f32_32x32x16_bf16 v[18:33], v[6:9], v[84:87], 0
	s_waitcnt lgkmcnt(1)
	s_waitcnt vmcnt(14)
	v_mfma_f32_32x32x16_bf16 v[18:33], v[62:65], v[88:91], v[18:33]
	s_waitcnt vmcnt(13)
	v_mfma_f32_32x32x16_bf16 v[2:17], v[6:9], v[92:95], 0
	s_waitcnt vmcnt(12)
	v_mfma_f32_32x32x16_bf16 v[2:17], v[62:65], v[96:99], v[2:17]
	ds_read_b128 v[66:69], v52
	s_waitcnt lgkmcnt(1)
	s_waitcnt vmcnt(11)
	v_mfma_f32_32x32x16_bf16 v[18:33], v[70:73], v[100:103], v[18:33]
	s_waitcnt vmcnt(10)
	v_mfma_f32_32x32x16_bf16 v[2:17], v[70:73], v[104:107], v[2:17]
	ds_read_b128 v[70:73], v53
	s_waitcnt lgkmcnt(1)
	s_waitcnt vmcnt(9)
	v_mfma_f32_32x32x16_bf16 v[18:33], v[66:69], v[108:111], v[18:33]
	s_waitcnt vmcnt(8)
	v_mfma_f32_32x32x16_bf16 v[2:17], v[66:69], v[112:115], v[2:17]
	ds_read_b128 v[66:69], v54
	s_waitcnt lgkmcnt(1)
	s_waitcnt vmcnt(7)
	v_mfma_f32_32x32x16_bf16 v[18:33], v[70:73], v[116:119], v[18:33]
	s_waitcnt vmcnt(6)
	v_mfma_f32_32x32x16_bf16 v[2:17], v[70:73], v[120:123], v[2:17]
	ds_read_b128 v[70:73], v55
	s_waitcnt lgkmcnt(1)
	s_waitcnt vmcnt(5)
	v_mfma_f32_32x32x16_bf16 v[18:33], v[66:69], v[124:127], v[18:33]
	s_waitcnt vmcnt(4)
	v_mfma_f32_32x32x16_bf16 v[2:17], v[66:69], v[128:131], v[2:17]
	s_waitcnt lgkmcnt(0)
	s_waitcnt vmcnt(3)
	v_mfma_f32_32x32x16_bf16 v[18:33], v[70:73], v[132:135], v[18:33]
	v_cmp_gt_i32_e32 vcc, s88, v46
	s_waitcnt vmcnt(2)
	v_mfma_f32_32x32x16_bf16 v[2:17], v[70:73], v[136:139], v[2:17]
	ds_read_b128 v[62:65], v56
	s_waitcnt lgkmcnt(0)
	s_waitcnt vmcnt(1)
	v_mfma_f32_32x32x16_bf16 v[18:33], v[62:65], v[140:143], v[18:33]
	s_waitcnt vmcnt(0)
	v_mfma_f32_32x32x16_bf16 v[2:17], v[62:65], v[150:153], v[2:17]
	s_nop 8
	ds_write2st64_b32 v48, v18, v19 offset1:1
	ds_write2st64_b32 v48, v20, v21 offset0:2 offset1:3
	ds_write2st64_b32 v48, v22, v23 offset0:4 offset1:5
	ds_write2st64_b32 v48, v24, v25 offset0:6 offset1:7
	ds_write2st64_b32 v48, v26, v27 offset0:8 offset1:9
	ds_write2st64_b32 v48, v28, v29 offset0:10 offset1:11
	ds_write2st64_b32 v48, v30, v31 offset0:12 offset1:13
	ds_write2st64_b32 v48, v32, v33 offset0:14 offset1:15
	ds_write2st64_b32 v48, v2, v3 offset0:16 offset1:17
	ds_write2st64_b32 v48, v4, v5 offset0:18 offset1:19
	ds_write2st64_b32 v48, v6, v7 offset0:20 offset1:21
	ds_write2st64_b32 v48, v8, v9 offset0:22 offset1:23
	ds_write2st64_b32 v48, v10, v11 offset0:24 offset1:25
	ds_write2st64_b32 v48, v12, v13 offset0:26 offset1:27
	ds_write2st64_b32 v48, v14, v15 offset0:28 offset1:29
	ds_write2st64_b32 v48, v16, v17 offset0:30 offset1:31
	s_waitcnt lgkmcnt(0)
	s_barrier
	s_and_saveexec_b64 s[0:1], vcc
	s_cbranch_execz .LBB0_1757
	ds_read2st64_b32 v[2:3], v57 offset1:1
	ds_read2st64_b32 v[4:5], v57 offset0:64 offset1:65
	ds_read2st64_b32 v[6:7], v57 offset0:128 offset1:129
	ds_read2st64_b32 v[8:9], v57 offset0:192 offset1:193
	ds_read2st64_b32 v[14:15], v57 offset0:32 offset1:33
	ds_read2st64_b32 v[16:17], v57 offset0:34 offset1:35
	ds_read2st64_b32 v[18:19], v57 offset0:2 offset1:3
	s_waitcnt lgkmcnt(6)
	v_mov_b32_e32 v20, v3
	v_mov_b32_e32 v21, v2
	v_pk_add_f32 v[2:3], v[20:21], 0 op_sel_hi:[1,0]
	s_waitcnt lgkmcnt(2)
	v_mov_b32_e32 v20, v15
	v_mov_b32_e32 v21, v14
	v_pk_add_f32 v[2:3], v[2:3], v[20:21]
	ds_read2st64_b32 v[14:15], v57 offset0:96 offset1:97
	ds_read2st64_b32 v[20:21], v57 offset0:98 offset1:99
	ds_read2st64_b32 v[22:23], v57 offset0:66 offset1:67
	v_mov_b32_e32 v24, v5
	v_mov_b32_e32 v25, v4
	v_pk_add_f32 v[2:3], v[2:3], v[24:25]
	s_waitcnt lgkmcnt(2)
	v_mov_b32_e32 v4, v15
	v_mov_b32_e32 v5, v14
	v_pk_add_f32 v[2:3], v[2:3], v[4:5]
	ds_read2st64_b32 v[4:5], v57 offset0:160 offset1:161
	ds_read2st64_b32 v[14:15], v57 offset0:162 offset1:163
	ds_read2st64_b32 v[24:25], v57 offset0:130 offset1:131
	v_mov_b32_e32 v26, v7
	v_mov_b32_e32 v27, v6
	v_pk_add_f32 v[2:3], v[2:3], v[26:27]
	s_waitcnt lgkmcnt(2)
	v_mov_b32_e32 v6, v5
	v_mov_b32_e32 v7, v4
	v_pk_add_f32 v[2:3], v[2:3], v[6:7]
	ds_read2st64_b32 v[4:5], v57 offset0:224 offset1:225
	ds_read2st64_b32 v[6:7], v57 offset0:226 offset1:227
	ds_read2st64_b32 v[26:27], v57 offset0:194 offset1:195
	v_mov_b32_e32 v28, v9
	v_mov_b32_e32 v29, v8
	v_pk_add_f32 v[2:3], v[2:3], v[28:29]
	s_waitcnt lgkmcnt(2)
	v_mov_b32_e32 v8, v5
	v_mov_b32_e32 v9, v4
	v_pk_add_f32 v[2:3], v[2:3], v[8:9]
	v_ashrrev_i32_e32 v47, 31, v46
	v_cmp_lt_f32_e32 vcc, 0, v3
	v_lshlrev_b64 v[10:11], 2, v[46:47]
	v_lshl_add_u64 v[12:13], v[36:37], 0, v[10:11]
	v_cndmask_b32_e32 v3, 0, v3, vcc
	v_cmp_lt_f32_e32 vcc, 0, v2
	v_mul_f32_e32 v3, v3, v3
	global_store_dword v[12:13], v3, off
	v_cndmask_b32_e32 v2, 0, v2, vcc
	v_mul_f32_e32 v4, v2, v2
	v_lshl_add_u64 v[2:3], v[38:39], 0, v[10:11]
	global_store_dword v[2:3], v4, off
	v_mov_b32_e32 v4, v19
	v_mov_b32_e32 v5, v18
	v_pk_add_f32 v[4:5], v[4:5], 0 op_sel_hi:[1,0]
	v_mov_b32_e32 v8, v17
	v_mov_b32_e32 v9, v16
	v_pk_add_f32 v[4:5], v[4:5], v[8:9]
	v_mov_b32_e32 v8, v23
	v_mov_b32_e32 v9, v22
	v_pk_add_f32 v[4:5], v[4:5], v[8:9]
	v_mov_b32_e32 v8, v21
	v_mov_b32_e32 v9, v20
	v_pk_add_f32 v[4:5], v[4:5], v[8:9]
	v_mov_b32_e32 v8, v25
	v_mov_b32_e32 v9, v24
	v_pk_add_f32 v[4:5], v[4:5], v[8:9]
	v_mov_b32_e32 v8, v15
	v_mov_b32_e32 v9, v14
	v_pk_add_f32 v[4:5], v[4:5], v[8:9]
	s_waitcnt lgkmcnt(0)
	v_mov_b32_e32 v8, v27
	v_mov_b32_e32 v9, v26
	v_pk_add_f32 v[4:5], v[4:5], v[8:9]
	v_mov_b32_e32 v8, v7
	v_mov_b32_e32 v9, v6
	v_pk_add_f32 v[4:5], v[4:5], v[8:9]
	v_lshl_add_u64 v[2:3], v[40:41], 0, v[10:11]
	v_cmp_lt_f32_e32 vcc, 0, v5
	s_nop 1
	v_cndmask_b32_e32 v5, 0, v5, vcc
	v_mul_f32_e32 v5, v5, v5
	v_cmp_lt_f32_e32 vcc, 0, v4
	global_store_dword v[2:3], v5, off
	s_nop 0
	v_cndmask_b32_e32 v2, 0, v4, vcc
	v_mul_f32_e32 v4, v2, v2
	v_lshl_add_u64 v[2:3], v[42:43], 0, v[10:11]
	global_store_dword v[2:3], v4, off
	s_branch .LBB0_1757

;     ...
;     for (int it = (int)blockIdx.x - wg_lo; it < NIT; it += wg_n) { const int ks = it / nT, it2 = it % nT, mb = it2 % nMb, nbk = it2 / nMb, row0 = 32 * mb, col0 = 64 * nbk, kbeg = (ks * 8 + wave) * KW;
;         f32x16 acc0 = {}, acc1 = {};
;         const bf16* b0p = Bt + (size_t)(col0 + r32) * K + 16 * hh + kbeg; const bf16* b1p = b0p + (size_t)32 * K; const float* af = (const float*)Av + (size_t)(row0 + r32) * lda + 16 * hh + kbeg; const bf16* ab = (const bf16*)Av + (size_t)(row0 + r32) * lda + 16 * hh + kbeg;
; #pragma unroll
;         for (int k0 = 0; k0 < KW; k0 += 32) { bf16x8 a0, a1;
;           if (ABF) { a0 = *(const bf16x8*)(ab + k0); a1 = *(const bf16x8*)(ab + k0 + 8); } else {
;             const f32x4 x0 = *(const f32x4*)(af + k0), x1 = *(const f32x4*)(af + k0 + 4), x2 = *(const f32x4*)(af + k0 + 8), x3 = *(const f32x4*)(af + k0 + 12);
;             const u32x4_t p0 = {cvtpk(x0[0], x0[1]), cvtpk(x0[2], x0[3]), cvtpk(x1[0], x1[1]), cvtpk(x1[2], x1[3])}, p1 = {cvtpk(x2[0], x2[1]), cvtpk(x2[2], x2[3]), cvtpk(x3[0], x3[1]), cvtpk(x3[2], x3[3])};
;             a0 = __builtin_bit_cast(bf16x8, p0); a1 = __builtin_bit_cast(bf16x8, p1); }
;             const bf16x8 b00 = *(const bf16x8*)(b0p + k0), b01 = *(const bf16x8*)(b0p + k0 + 8), b10 = *(const bf16x8*)(b1p + k0), b11 = *(const bf16x8*)(b1p + k0 + 8);
;             acc0 = __builtin_amdgcn_mfma_f32_32x32x16_bf16(a0, b00, acc0, 0, 0, 0); acc0 = __builtin_amdgcn_mfma_f32_32x32x16_bf16(a1, b01, acc0, 0, 0, 0);
;             acc1 = __builtin_amdgcn_mfma_f32_32x32x16_bf16(a0, b10, acc1, 0, 0, 0); acc1 = __builtin_amdgcn_mfma_f32_32x32x16_bf16(a1, b11, acc1, 0, 0, 0); }
; #pragma unroll
;         for (int rg = 0; rg < 16; ++rg) { red[wave * 2048 + rg * 64 + lane] = acc0[rg]; red[wave * 2048 + (16 + rg) * 64 + lane] = acc1[rg]; }
.LBB0_1971:
	s_ashr_i32 s2, s5, 31
	s_lshr_b32 s2, s2, 25
	s_add_i32 s3, s5, s2
	s_and_b32 s2, s3, 0xff80
	s_sub_i32 s2, s5, s2
	s_bfe_i32 s6, s2, 0x80000
	s_bfe_u32 s6, s6, 0x3000c
	s_add_i32 s6, s2, s6
	s_bfe_i32 s7, s6, 0x80000
	s_and_b32 s6, s6, 0xf8
	s_sub_i32 s2, s2, s6
	s_sext_i32_i16 s7, s7
	s_sext_i32_i8 s2, s2
	s_lshl_b32 s6, s2, 5
	s_lshl_b32 s2, s7, 3
	s_andn2_b32 s2, s2, 63
	s_lshl_b32 s3, s3, 3
	v_or_b32_e32 v2, s2, v44
	s_and_b32 s3, s3, 0xfffffc00
	v_ashrrev_i32_e32 v3, 31, v2
	s_add_i32 s8, s3, s4
	v_lshlrev_b64 v[2:3], 13, v[2:3]
	v_lshl_add_u64 v[2:3], v[34:35], 0, v[2:3]
	s_ashr_i32 s9, s8, 31
	v_lshl_add_u64 v[38:39], s[8:9], 1, v[2:3]
	v_or_b32_e32 v2, s6, v44
	v_ashrrev_i32_e32 v3, 31, v2
	v_lshlrev_b64 v[2:3], 14, v[2:3]
	v_lshl_add_u64 v[2:3], v[36:37], 0, v[2:3]
	v_lshl_add_u64 v[42:43], s[8:9], 2, v[2:3]
	global_load_dwordx4 v[84:87], v[42:43], off offset:48
	global_load_dwordx4 v[88:91], v[42:43], off offset:32
	global_load_dwordx4 v[92:95], v[42:43], off offset:16
	global_load_dwordx4 v[96:99], v[42:43], off
	s_mov_b32 s3, 0x40000
	v_add_co_u32_e32 v40, vcc, s3, v38
	s_nop 1
	global_load_dwordx4 v[100:103], v[38:39], off
	global_load_dwordx4 v[104:107], v[38:39], off offset:16
	v_addc_co_u32_e32 v41, vcc, 0, v39, vcc
	global_load_dwordx4 v[108:111], v[40:41], off
	global_load_dwordx4 v[112:115], v[40:41], off offset:16
	global_load_dwordx4 v[116:119], v[42:43], off offset:176
	global_load_dwordx4 v[120:123], v[42:43], off offset:160
	global_load_dwordx4 v[124:127], v[42:43], off offset:144
	global_load_dwordx4 v[128:131], v[42:43], off offset:128
	global_load_dwordx4 v[132:135], v[38:39], off offset:64
	global_load_dwordx4 v[136:139], v[38:39], off offset:80
	global_load_dwordx4 v[140:143], v[40:41], off offset:64
	global_load_dwordx4 v[150:153], v[40:41], off offset:80
	s_waitcnt vmcnt(15)
	v_cvt_pk_bf16_f32 v52, v84, v85
	v_cvt_pk_bf16_f32 v53, v86, v87
	s_waitcnt vmcnt(12)
	v_cvt_pk_bf16_f32 v18, v96, v97
	v_cvt_pk_bf16_f32 v19, v98, v99
	v_cvt_pk_bf16_f32 v20, v92, v93
	v_cvt_pk_bf16_f32 v21, v94, v95
	v_cvt_pk_bf16_f32 v50, v88, v89
	v_cvt_pk_bf16_f32 v51, v90, v91
	s_waitcnt vmcnt(11)
	v_mfma_f32_32x32x16_bf16 v[2:17], v[18:21], v[100:103], 0
	s_waitcnt vmcnt(10)
	v_mfma_f32_32x32x16_bf16 v[2:17], v[50:53], v[104:107], v[2:17]
	s_waitcnt vmcnt(9)
	v_mfma_f32_32x32x16_bf16 v[18:33], v[18:21], v[108:111], 0
	s_waitcnt vmcnt(8)
	v_mfma_f32_32x32x16_bf16 v[18:33], v[50:53], v[112:115], v[18:33]
	s_waitcnt vmcnt(6)
	v_cvt_pk_bf16_f32 v54, v120, v121
	v_cvt_pk_bf16_f32 v55, v122, v123
	s_waitcnt vmcnt(4)
	v_cvt_pk_bf16_f32 v62, v128, v129
	v_cvt_pk_bf16_f32 v63, v130, v131
	v_cvt_pk_bf16_f32 v64, v124, v125
	v_cvt_pk_bf16_f32 v65, v126, v127
	v_cvt_pk_bf16_f32 v56, v116, v117
	v_cvt_pk_bf16_f32 v57, v118, v119
	s_waitcnt vmcnt(3)
	v_mfma_f32_32x32x16_bf16 v[2:17], v[62:65], v[132:135], v[2:17]
	s_waitcnt vmcnt(1)
	v_mfma_f32_32x32x16_bf16 v[18:33], v[62:65], v[140:143], v[18:33]
	v_mfma_f32_32x32x16_bf16 v[2:17], v[54:57], v[136:139], v[2:17]
	s_waitcnt vmcnt(0)
	v_mfma_f32_32x32x16_bf16 v[18:33], v[54:57], v[150:153], v[18:33]
	global_load_dwordx4 v[84:87], v[42:43], off offset:304
	global_load_dwordx4 v[88:91], v[42:43], off offset:288
	global_load_dwordx4 v[92:95], v[42:43], off offset:272
	global_load_dwordx4 v[96:99], v[42:43], off offset:256
	global_load_dwordx4 v[100:103], v[38:39], off offset:128
	global_load_dwordx4 v[104:107], v[38:39], off offset:144
	global_load_dwordx4 v[108:111], v[40:41], off offset:128
	global_load_dwordx4 v[112:115], v[40:41], off offset:144
	global_load_dwordx4 v[116:119], v[42:43], off offset:432
	global_load_dwordx4 v[120:123], v[42:43], off offset:416
	global_load_dwordx4 v[124:127], v[42:43], off offset:400
	global_load_dwordx4 v[128:131], v[42:43], off offset:384
	global_load_dwordx4 v[132:135], v[38:39], off offset:192
	global_load_dwordx4 v[136:139], v[38:39], off offset:208
	global_load_dwordx4 v[140:143], v[40:41], off offset:192
	global_load_dwordx4 v[150:153], v[40:41], off offset:208
	s_waitcnt vmcnt(14)
	v_cvt_pk_bf16_f32 v54, v88, v89
	v_cvt_pk_bf16_f32 v55, v90, v91
	s_waitcnt vmcnt(12)
	v_cvt_pk_bf16_f32 v62, v96, v97
	v_cvt_pk_bf16_f32 v63, v98, v99
	v_cvt_pk_bf16_f32 v64, v92, v93
	v_cvt_pk_bf16_f32 v65, v94, v95
	v_cvt_pk_bf16_f32 v56, v84, v85
	v_cvt_pk_bf16_f32 v57, v86, v87
	s_waitcnt vmcnt(11)
	v_mfma_f32_32x32x16_bf16 v[2:17], v[62:65], v[100:103], v[2:17]
	s_waitcnt vmcnt(9)
	v_mfma_f32_32x32x16_bf16 v[18:33], v[62:65], v[108:111], v[18:33]
	v_mfma_f32_32x32x16_bf16 v[2:17], v[54:57], v[104:107], v[2:17]
	s_waitcnt vmcnt(8)
	v_mfma_f32_32x32x16_bf16 v[18:33], v[54:57], v[112:115], v[18:33]
	s_waitcnt vmcnt(6)
	v_cvt_pk_bf16_f32 v54, v120, v121
	v_cvt_pk_bf16_f32 v55, v122, v123
	s_waitcnt vmcnt(4)
	v_cvt_pk_bf16_f32 v62, v128, v129
	v_cvt_pk_bf16_f32 v63, v130, v131
	v_cvt_pk_bf16_f32 v64, v124, v125
	v_cvt_pk_bf16_f32 v65, v126, v127
	v_cvt_pk_bf16_f32 v56, v116, v117
	v_cvt_pk_bf16_f32 v57, v118, v119
	s_waitcnt vmcnt(3)
	v_mfma_f32_32x32x16_bf16 v[2:17], v[62:65], v[132:135], v[2:17]
	s_waitcnt vmcnt(1)
	v_mfma_f32_32x32x16_bf16 v[18:33], v[62:65], v[140:143], v[18:33]
	v_mfma_f32_32x32x16_bf16 v[2:17], v[54:57], v[136:139], v[2:17]
	s_waitcnt vmcnt(0)
	v_mfma_f32_32x32x16_bf16 v[18:33], v[54:57], v[150:153], v[18:33]
	s_nop 9
	ds_write2st64_b32 v47, v2, v3 offset1:1
	s_nop 0
	ds_write2st64_b32 v47, v18, v19 offset0:16 offset1:17
	ds_write2st64_b32 v47, v4, v5 offset0:2 offset1:3
	ds_write2st64_b32 v47, v20, v21 offset0:18 offset1:19
	ds_write2st64_b32 v47, v6, v7 offset0:4 offset1:5
	ds_write2st64_b32 v47, v22, v23 offset0:20 offset1:21
	ds_write2st64_b32 v47, v8, v9 offset0:6 offset1:7
	ds_write2st64_b32 v47, v24, v25 offset0:22 offset1:23
	ds_write2st64_b32 v47, v10, v11 offset0:8 offset1:9
	ds_write2st64_b32 v47, v26, v27 offset0:24 offset1:25
	ds_write2st64_b32 v47, v12, v13 offset0:10 offset1:11
	ds_write2st64_b32 v47, v28, v29 offset0:26 offset1:27
	ds_write2st64_b32 v47, v14, v15 offset0:12 offset1:13
	ds_write2st64_b32 v47, v30, v31 offset0:28 offset1:29
	ds_write2st64_b32 v47, v16, v17 offset0:14 offset1:15
	ds_write2st64_b32 v47, v32, v33 offset0:30 offset1:31
	v_add_u32_e32 v4, s2, v45
	s_movk_i32 s2, 0x400
	v_cmp_gt_i32_e32 vcc, s2, v4
	s_waitcnt lgkmcnt(0)
	s_barrier
; __device__ __forceinline__ int crow(int r, int hi) { return (r & 3) + 8 * (r >> 2) + 4 * hi; }
; __device__ __forceinline__ int crow(int r, int hi) { return (r & 3) + 8 * (r >> 2) + 4 * hi; }
; __device__ __forceinline__ int crow(int r, int hi) { return (r & 3) + 8 * (r >> 2) + 4 * hi; }
; __device__ __forceinline__ int crow(int r, int hi) { return (r & 3) + 8 * (r >> 2) + 4 * hi; }
;     __device__ __forceinline__ void el(int row, int col, float v) const { if (col < nvalid) { if (act == 1) { v = v > 0.f ? v : 0.f; v = v * v; } C[(size_t)row * ldc + col] = v; } }
;     ...
; #pragma unroll
;         for (int q = 0; q < 4; ++q) { const int rr = 4 * wave + q; float v = 0.f;
; #pragma unroll
;             for (int w = 0; w < 8; ++w) v += red[w * 2048 + rr * 64 + lane];
;             E.el(row0 + crow(rr & 15, hh), col0 + (rr >> 4) * 32 + r32, v, r32); }
	s_and_saveexec_b64 s[2:3], vcc
	s_cbranch_execz .LBB0_1970
	ds_read2st64_b32 v[6:7], v48 offset1:32
	v_or_b32_e32 v2, s6, v46
	v_ashrrev_i32_e32 v5, 31, v4
	v_lshlrev_b64 v[4:5], 2, v[4:5]
	s_waitcnt lgkmcnt(0)
	v_add_f32_e32 v3, 0, v6
	v_add_f32_e32 v3, v3, v7
	ds_read2st64_b32 v[6:7], v48 offset0:64 offset1:96
	s_waitcnt lgkmcnt(0)
	v_add_f32_e32 v3, v3, v6
	v_add_f32_e32 v3, v3, v7
	ds_read2st64_b32 v[6:7], v48 offset0:128 offset1:160
	s_waitcnt lgkmcnt(0)
	v_add_f32_e32 v3, v3, v6
	v_add_f32_e32 v3, v3, v7
	ds_read2st64_b32 v[6:7], v48 offset0:192 offset1:224
	s_waitcnt lgkmcnt(0)
	v_add_f32_e32 v3, v3, v6
	v_add_f32_e32 v8, v3, v7
	v_ashrrev_i32_e32 v3, 31, v2
	v_lshlrev_b64 v[6:7], 12, v[2:3]
	v_lshl_add_u64 v[6:7], s[0:1], 0, v[6:7]
	v_lshl_add_u64 v[6:7], v[6:7], 0, v[4:5]
	global_atomic_add_f32 v[6:7], v8, off
	ds_read2st64_b32 v[6:7], v48 offset0:1 offset1:33
	s_waitcnt lgkmcnt(0)
	v_add_f32_e32 v3, 0, v6
	v_add_f32_e32 v3, v3, v7
	ds_read2st64_b32 v[6:7], v48 offset0:65 offset1:97
	s_waitcnt lgkmcnt(0)
	v_add_f32_e32 v3, v3, v6
	v_add_f32_e32 v3, v3, v7
	ds_read2st64_b32 v[6:7], v48 offset0:129 offset1:161
	s_waitcnt lgkmcnt(0)
	v_add_f32_e32 v3, v3, v6
	v_add_f32_e32 v3, v3, v7
	ds_read2st64_b32 v[6:7], v48 offset0:193 offset1:225
	s_waitcnt lgkmcnt(0)
	v_add_f32_e32 v3, v3, v6
	v_or_b32_e32 v6, 1, v2
	v_add_f32_e32 v3, v3, v7
	v_ashrrev_i32_e32 v7, 31, v6
	v_lshlrev_b64 v[6:7], 12, v[6:7]
	v_lshl_add_u64 v[6:7], s[0:1], 0, v[6:7]
	v_lshl_add_u64 v[6:7], v[6:7], 0, v[4:5]
	global_atomic_add_f32 v[6:7], v3, off
	ds_read2st64_b32 v[6:7], v48 offset0:2 offset1:34
	s_waitcnt lgkmcnt(0)
	v_add_f32_e32 v3, 0, v6
	v_add_f32_e32 v3, v3, v7
	ds_read2st64_b32 v[6:7], v48 offset0:66 offset1:98
	s_waitcnt lgkmcnt(0)
	v_add_f32_e32 v3, v3, v6
	v_add_f32_e32 v3, v3, v7
	ds_read2st64_b32 v[6:7], v48 offset0:130 offset1:162
	s_waitcnt lgkmcnt(0)
	v_add_f32_e32 v3, v3, v6
	v_add_f32_e32 v3, v3, v7
	ds_read2st64_b32 v[6:7], v48 offset0:194 offset1:226
	s_waitcnt lgkmcnt(0)
	v_add_f32_e32 v3, v3, v6
	v_or_b32_e32 v6, 2, v2
	v_add_f32_e32 v3, v3, v7
	v_ashrrev_i32_e32 v7, 31, v6
	v_lshlrev_b64 v[6:7], 12, v[6:7]
	v_lshl_add_u64 v[6:7], s[0:1], 0, v[6:7]
	v_lshl_add_u64 v[6:7], v[6:7], 0, v[4:5]
	global_atomic_add_f32 v[6:7], v3, off
	ds_read2st64_b32 v[6:7], v48 offset0:3 offset1:35
	v_or_b32_e32 v2, 3, v2
	s_waitcnt lgkmcnt(0)
	v_add_f32_e32 v3, 0, v6
	v_add_f32_e32 v3, v3, v7
	ds_read2st64_b32 v[6:7], v48 offset0:67 offset1:99
	s_waitcnt lgkmcnt(0)
	v_add_f32_e32 v3, v3, v6
	v_add_f32_e32 v3, v3, v7
	ds_read2st64_b32 v[6:7], v48 offset0:131 offset1:163
	s_waitcnt lgkmcnt(0)
	v_add_f32_e32 v3, v3, v6
	v_add_f32_e32 v3, v3, v7
	ds_read2st64_b32 v[6:7], v48 offset0:195 offset1:227
	s_waitcnt lgkmcnt(0)
	v_add_f32_e32 v3, v3, v6
	v_add_f32_e32 v6, v3, v7
	v_ashrrev_i32_e32 v3, 31, v2
	v_lshlrev_b64 v[2:3], 12, v[2:3]
	v_lshl_add_u64 v[2:3], s[0:1], 0, v[2:3]
	v_lshl_add_u64 v[2:3], v[2:3], 0, v[4:5]
	global_atomic_add_f32 v[2:3], v6, off
	s_branch .LBB0_1970
